# epilogue skew in in-proj and ff1 GEMMs: wave halves keep their one-barrier offset through the epilogue (on top of v42)
# baseline (speedup 1.0000x reference)
.LBB0_233:
	ds_read_b128 v[130:133], v213
	ds_read_b128 v[134:137], v214
	ds_read_b128 v[138:141], v215
	ds_read_b128 v[142:145], v216
	ds_read_b128 v[146:149], v217
	ds_read_b128 v[150:153], v218
	ds_read_b128 v[154:157], v219
	ds_read_b128 v[158:161], v220
	s_add_i32 s4, s33, 0xffffe080
	s_cmp_eq_u32 s58, 12
	s_cselect_b32 s61, s18, s4
	s_cselect_b32 s60, s19, s57
	s_add_i32 s59, s61, 0x80
	s_mov_b32 s4, s70
	s_mov_b32 m0, s38
	ds_read_b128 v[162:165], v221
	ds_read_b128 v[166:169], v221 offset:2048
	ds_read_b128 v[170:173], v222
	ds_read_b128 v[174:177], v222 offset:2048
	ds_read_b128 v[178:181], v221 offset:4096
	ds_read_b128 v[182:185], v221 offset:6144
	ds_read_b128 v[186:189], v222 offset:4096
	ds_read_b128 v[190:193], v222 offset:6144
	buffer_load_dwordx4 v207, s[4:7], s33 offen lds
	s_mov_b32 m0, s41
	s_nop 0
	buffer_load_dwordx4 v209, s[4:7], s33 offen lds
	s_waitcnt vmcnt(8)
	s_waitcnt lgkmcnt(0)
	s_barrier
	s_setprio 1
	s_waitcnt lgkmcnt(7)
	v_mfma_f32_16x16x32_bf16 v[114:117], v[130:133], v[162:165], v[114:117]
	v_mfma_f32_16x16x32_bf16 v[110:113], v[138:141], v[162:165], v[110:113]
	s_waitcnt lgkmcnt(6)
	v_mfma_f32_16x16x32_bf16 v[106:109], v[130:133], v[166:169], v[106:109]
	v_mfma_f32_16x16x32_bf16 v[102:105], v[138:141], v[166:169], v[102:105]
	s_waitcnt lgkmcnt(3)
	v_mfma_f32_16x16x32_bf16 v[98:101], v[130:133], v[178:181], v[98:101]
	v_mfma_f32_16x16x32_bf16 v[94:97], v[138:141], v[178:181], v[94:97]
	s_waitcnt lgkmcnt(2)
	v_mfma_f32_16x16x32_bf16 v[90:93], v[130:133], v[182:185], v[90:93]
	v_mfma_f32_16x16x32_bf16 v[86:89], v[138:141], v[182:185], v[86:89]
	v_mfma_f32_16x16x32_bf16 v[114:117], v[134:137], v[170:173], v[114:117]
	v_mfma_f32_16x16x32_bf16 v[110:113], v[142:145], v[170:173], v[110:113]
	v_mfma_f32_16x16x32_bf16 v[106:109], v[134:137], v[174:177], v[106:109]
	v_mfma_f32_16x16x32_bf16 v[102:105], v[142:145], v[174:177], v[102:105]
	s_waitcnt lgkmcnt(1)
	v_mfma_f32_16x16x32_bf16 v[98:101], v[134:137], v[186:189], v[98:101]
	v_mfma_f32_16x16x32_bf16 v[94:97], v[142:145], v[186:189], v[94:97]
	s_waitcnt lgkmcnt(0)
	v_mfma_f32_16x16x32_bf16 v[90:93], v[134:137], v[190:193], v[90:93]
	v_mfma_f32_16x16x32_bf16 v[86:89], v[142:145], v[190:193], v[86:89]
	s_setprio 0
	s_setprio 1
	v_mfma_f32_16x16x32_bf16 v[82:85], v[146:149], v[162:165], v[82:85]
	v_mfma_f32_16x16x32_bf16 v[74:77], v[154:157], v[162:165], v[74:77]
	v_mfma_f32_16x16x32_bf16 v[70:73], v[146:149], v[166:169], v[70:73]
	v_mfma_f32_16x16x32_bf16 v[66:69], v[154:157], v[166:169], v[66:69]
	v_mfma_f32_16x16x32_bf16 v[62:65], v[146:149], v[178:181], v[62:65]
	v_mfma_f32_16x16x32_bf16 v[58:61], v[154:157], v[178:181], v[58:61]
	v_mfma_f32_16x16x32_bf16 v[54:57], v[146:149], v[182:185], v[54:57]
	v_mfma_f32_16x16x32_bf16 v[50:53], v[154:157], v[182:185], v[50:53]
	v_mfma_f32_16x16x32_bf16 v[82:85], v[150:153], v[170:173], v[82:85]
	v_mfma_f32_16x16x32_bf16 v[74:77], v[158:161], v[170:173], v[74:77]
	v_mfma_f32_16x16x32_bf16 v[70:73], v[150:153], v[174:177], v[70:73]
	v_mfma_f32_16x16x32_bf16 v[66:69], v[158:161], v[174:177], v[66:69]
	v_mfma_f32_16x16x32_bf16 v[62:65], v[150:153], v[186:189], v[62:65]
	v_mfma_f32_16x16x32_bf16 v[58:61], v[158:161], v[186:189], v[58:61]
	v_mfma_f32_16x16x32_bf16 v[54:57], v[150:153], v[190:193], v[54:57]
	v_mfma_f32_16x16x32_bf16 v[50:53], v[158:161], v[190:193], v[50:53]
	s_setprio 0
	s_barrier
	s_mov_b32 m0, s21
	ds_read_b128 v[162:165], v221 offset:16384
	ds_read_b128 v[166:169], v221 offset:18432
	ds_read_b128 v[170:173], v222 offset:16384
	ds_read_b128 v[174:177], v222 offset:18432
	ds_read_b128 v[178:181], v221 offset:20480
	ds_read_b128 v[182:185], v221 offset:22528
	ds_read_b128 v[186:189], v222 offset:20480
	ds_read_b128 v[190:193], v222 offset:22528
	buffer_load_dwordx4 v208, s[4:7], s60 offen lds
	s_mov_b32 m0, s22
	s_add_i32 s62, s60, 0x40000
	buffer_load_dwordx4 v210, s[4:7], s60 offen lds
	s_mov_b32 m0, s23
	s_nop 0
	buffer_load_dwordx4 v208, s[4:7], s62 offen lds
	s_mov_b32 m0, s24
	s_nop 0
	buffer_load_dwordx4 v210, s[4:7], s62 offen lds
	s_mov_b32 m0, s20
	s_nop 0
	buffer_load_dwordx4 v207, s[4:7], s61 offen lds
	s_mov_b32 m0, s25
	s_nop 0
	buffer_load_dwordx4 v209, s[4:7], s61 offen lds
	s_waitcnt vmcnt(8)
	s_waitcnt lgkmcnt(0)
	s_barrier
	s_setprio 1
	s_waitcnt lgkmcnt(7)
	v_mfma_f32_16x16x32_bf16 v[78:81], v[130:133], v[162:165], v[78:81]
	v_mfma_f32_16x16x32_bf16 v[46:49], v[138:141], v[162:165], v[46:49]
	s_waitcnt lgkmcnt(6)
	v_mfma_f32_16x16x32_bf16 v[42:45], v[130:133], v[166:169], v[42:45]
	v_mfma_f32_16x16x32_bf16 v[38:41], v[138:141], v[166:169], v[38:41]
	s_waitcnt lgkmcnt(3)
	v_mfma_f32_16x16x32_bf16 v[34:37], v[130:133], v[178:181], v[34:37]
	v_mfma_f32_16x16x32_bf16 v[30:33], v[138:141], v[178:181], v[30:33]
	s_waitcnt lgkmcnt(2)
	v_mfma_f32_16x16x32_bf16 v[26:29], v[130:133], v[182:185], v[26:29]
	v_mfma_f32_16x16x32_bf16 v[22:25], v[138:141], v[182:185], v[22:25]
	v_mfma_f32_16x16x32_bf16 v[78:81], v[134:137], v[170:173], v[78:81]
	v_mfma_f32_16x16x32_bf16 v[46:49], v[142:145], v[170:173], v[46:49]
	v_mfma_f32_16x16x32_bf16 v[42:45], v[134:137], v[174:177], v[42:45]
	v_mfma_f32_16x16x32_bf16 v[38:41], v[142:145], v[174:177], v[38:41]
	s_waitcnt lgkmcnt(1)
	v_mfma_f32_16x16x32_bf16 v[34:37], v[134:137], v[186:189], v[34:37]
	v_mfma_f32_16x16x32_bf16 v[30:33], v[142:145], v[186:189], v[30:33]
	s_waitcnt lgkmcnt(0)
	v_mfma_f32_16x16x32_bf16 v[26:29], v[134:137], v[190:193], v[26:29]
	v_mfma_f32_16x16x32_bf16 v[22:25], v[142:145], v[190:193], v[22:25]
	s_setprio 0
	s_setprio 1
	v_mfma_f32_16x16x32_bf16 v[18:21], v[146:149], v[162:165], v[18:21]
	v_mfma_f32_16x16x32_bf16 v[14:17], v[154:157], v[162:165], v[14:17]
	v_mfma_f32_16x16x32_bf16 v[10:13], v[146:149], v[166:169], v[10:13]
	v_mfma_f32_16x16x32_bf16 v[6:9], v[154:157], v[166:169], v[6:9]
	v_mfma_f32_16x16x32_bf16 v[2:5], v[146:149], v[178:181], v[2:5]
	v_mfma_f32_16x16x32_bf16 v[126:129], v[154:157], v[178:181], v[126:129]
	v_mfma_f32_16x16x32_bf16 v[122:125], v[146:149], v[182:185], v[122:125]
	v_mfma_f32_16x16x32_bf16 v[118:121], v[154:157], v[182:185], v[118:121]
	v_mfma_f32_16x16x32_bf16 v[18:21], v[150:153], v[170:173], v[18:21]
	v_mfma_f32_16x16x32_bf16 v[14:17], v[158:161], v[170:173], v[14:17]
	v_mfma_f32_16x16x32_bf16 v[10:13], v[150:153], v[174:177], v[10:13]
	v_mfma_f32_16x16x32_bf16 v[6:9], v[158:161], v[174:177], v[6:9]
	v_mfma_f32_16x16x32_bf16 v[2:5], v[150:153], v[186:189], v[2:5]
	v_mfma_f32_16x16x32_bf16 v[126:129], v[158:161], v[186:189], v[126:129]
	v_mfma_f32_16x16x32_bf16 v[122:125], v[150:153], v[190:193], v[122:125]
	v_mfma_f32_16x16x32_bf16 v[118:121], v[158:161], v[190:193], v[118:121]
	s_setprio 0
	s_barrier
	ds_read_b128 v[130:133], v194
	ds_read_b128 v[134:137], v224
	ds_read_b128 v[138:141], v225
	ds_read_b128 v[142:145], v228
	ds_read_b128 v[146:149], v229
	ds_read_b128 v[150:153], v230
	ds_read_b128 v[154:157], v231
	ds_read_b128 v[158:161], v233
	s_addk_i32 s61, 0x2000
	s_mov_b32 m0, s26
	ds_read_b128 v[162:165], v221 offset:32768
	ds_read_b128 v[166:169], v221 offset:34816
	ds_read_b128 v[170:173], v222 offset:32768
	ds_read_b128 v[174:177], v222 offset:34816
	ds_read_b128 v[178:181], v221 offset:36864
	ds_read_b128 v[182:185], v221 offset:38912
	ds_read_b128 v[186:189], v222 offset:36864
	ds_read_b128 v[190:193], v222 offset:38912
	buffer_load_dwordx4 v207, s[4:7], s61 offen lds
	s_mov_b32 m0, s27
	s_nop 0
	buffer_load_dwordx4 v209, s[4:7], s61 offen lds
	s_waitcnt vmcnt(8)
	s_waitcnt lgkmcnt(0)
	s_barrier
	s_setprio 1
	s_waitcnt lgkmcnt(7)
	v_mfma_f32_16x16x32_bf16 v[114:117], v[130:133], v[162:165], v[114:117]
	v_mfma_f32_16x16x32_bf16 v[110:113], v[138:141], v[162:165], v[110:113]
	s_waitcnt lgkmcnt(6)
	v_mfma_f32_16x16x32_bf16 v[106:109], v[130:133], v[166:169], v[106:109]
	v_mfma_f32_16x16x32_bf16 v[102:105], v[138:141], v[166:169], v[102:105]
	s_waitcnt lgkmcnt(3)
	v_mfma_f32_16x16x32_bf16 v[98:101], v[130:133], v[178:181], v[98:101]
	v_mfma_f32_16x16x32_bf16 v[94:97], v[138:141], v[178:181], v[94:97]
	s_waitcnt lgkmcnt(2)
	v_mfma_f32_16x16x32_bf16 v[90:93], v[130:133], v[182:185], v[90:93]
	v_mfma_f32_16x16x32_bf16 v[86:89], v[138:141], v[182:185], v[86:89]
	v_mfma_f32_16x16x32_bf16 v[114:117], v[134:137], v[170:173], v[114:117]
	v_mfma_f32_16x16x32_bf16 v[110:113], v[142:145], v[170:173], v[110:113]
	v_mfma_f32_16x16x32_bf16 v[106:109], v[134:137], v[174:177], v[106:109]
	v_mfma_f32_16x16x32_bf16 v[102:105], v[142:145], v[174:177], v[102:105]
	s_waitcnt lgkmcnt(1)
	v_mfma_f32_16x16x32_bf16 v[98:101], v[134:137], v[186:189], v[98:101]
	v_mfma_f32_16x16x32_bf16 v[94:97], v[142:145], v[186:189], v[94:97]
	s_waitcnt lgkmcnt(0)
	v_mfma_f32_16x16x32_bf16 v[90:93], v[134:137], v[190:193], v[90:93]
	v_mfma_f32_16x16x32_bf16 v[86:89], v[142:145], v[190:193], v[86:89]
	s_setprio 0
	s_setprio 1
	v_mfma_f32_16x16x32_bf16 v[82:85], v[146:149], v[162:165], v[82:85]
	v_mfma_f32_16x16x32_bf16 v[74:77], v[154:157], v[162:165], v[74:77]
	v_mfma_f32_16x16x32_bf16 v[70:73], v[146:149], v[166:169], v[70:73]
	v_mfma_f32_16x16x32_bf16 v[66:69], v[154:157], v[166:169], v[66:69]
	v_mfma_f32_16x16x32_bf16 v[62:65], v[146:149], v[178:181], v[62:65]
	v_mfma_f32_16x16x32_bf16 v[58:61], v[154:157], v[178:181], v[58:61]
	v_mfma_f32_16x16x32_bf16 v[54:57], v[146:149], v[182:185], v[54:57]
	v_mfma_f32_16x16x32_bf16 v[50:53], v[154:157], v[182:185], v[50:53]
	v_mfma_f32_16x16x32_bf16 v[82:85], v[150:153], v[170:173], v[82:85]
	v_mfma_f32_16x16x32_bf16 v[74:77], v[158:161], v[170:173], v[74:77]
	v_mfma_f32_16x16x32_bf16 v[70:73], v[150:153], v[174:177], v[70:73]
	v_mfma_f32_16x16x32_bf16 v[66:69], v[158:161], v[174:177], v[66:69]
	v_mfma_f32_16x16x32_bf16 v[62:65], v[150:153], v[186:189], v[62:65]
	v_mfma_f32_16x16x32_bf16 v[58:61], v[158:161], v[186:189], v[58:61]
	v_mfma_f32_16x16x32_bf16 v[54:57], v[150:153], v[190:193], v[54:57]
	v_mfma_f32_16x16x32_bf16 v[50:53], v[158:161], v[190:193], v[50:53]
	s_setprio 0
	s_barrier
	s_mov_b32 m0, s29
	s_add_i32 s61, s60, 0x80
	ds_read_b128 v[162:165], v221 offset:49152
	ds_read_b128 v[166:169], v221 offset:51200
	ds_read_b128 v[170:173], v222 offset:49152
	ds_read_b128 v[174:177], v222 offset:51200
	ds_read_b128 v[178:181], v221 offset:53248
	ds_read_b128 v[182:185], v221 offset:55296
	ds_read_b128 v[186:189], v222 offset:53248
	ds_read_b128 v[190:193], v222 offset:55296
	buffer_load_dwordx4 v208, s[4:7], s61 offen lds
	s_mov_b32 m0, s30
	s_add_i32 s60, s60, 0x40080
	buffer_load_dwordx4 v210, s[4:7], s61 offen lds
	s_mov_b32 m0, s35
	s_nop 0
	buffer_load_dwordx4 v208, s[4:7], s60 offen lds
	s_mov_b32 m0, s36
	s_nop 0
	buffer_load_dwordx4 v210, s[4:7], s60 offen lds
	s_mov_b32 m0, s31
	s_nop 0
	buffer_load_dwordx4 v207, s[4:7], s59 offen lds
	s_mov_b32 m0, s34
	s_nop 0
	buffer_load_dwordx4 v209, s[4:7], s59 offen lds
	s_waitcnt vmcnt(8)
	s_waitcnt lgkmcnt(0)
	s_barrier
	s_setprio 1
	s_waitcnt lgkmcnt(7)
	v_mfma_f32_16x16x32_bf16 v[78:81], v[130:133], v[162:165], v[78:81]
	v_mfma_f32_16x16x32_bf16 v[46:49], v[138:141], v[162:165], v[46:49]
	s_waitcnt lgkmcnt(6)
	v_mfma_f32_16x16x32_bf16 v[42:45], v[130:133], v[166:169], v[42:45]
	v_mfma_f32_16x16x32_bf16 v[38:41], v[138:141], v[166:169], v[38:41]
	s_waitcnt lgkmcnt(3)
	v_mfma_f32_16x16x32_bf16 v[34:37], v[130:133], v[178:181], v[34:37]
	v_mfma_f32_16x16x32_bf16 v[30:33], v[138:141], v[178:181], v[30:33]
	s_waitcnt lgkmcnt(2)
	v_mfma_f32_16x16x32_bf16 v[26:29], v[130:133], v[182:185], v[26:29]
	v_mfma_f32_16x16x32_bf16 v[22:25], v[138:141], v[182:185], v[22:25]
	v_mfma_f32_16x16x32_bf16 v[78:81], v[134:137], v[170:173], v[78:81]
	v_mfma_f32_16x16x32_bf16 v[46:49], v[142:145], v[170:173], v[46:49]
	v_mfma_f32_16x16x32_bf16 v[42:45], v[134:137], v[174:177], v[42:45]
	v_mfma_f32_16x16x32_bf16 v[38:41], v[142:145], v[174:177], v[38:41]
	s_waitcnt lgkmcnt(1)
	v_mfma_f32_16x16x32_bf16 v[34:37], v[134:137], v[186:189], v[34:37]
	v_mfma_f32_16x16x32_bf16 v[30:33], v[142:145], v[186:189], v[30:33]
	s_waitcnt lgkmcnt(0)
	v_mfma_f32_16x16x32_bf16 v[26:29], v[134:137], v[190:193], v[26:29]
	v_mfma_f32_16x16x32_bf16 v[22:25], v[142:145], v[190:193], v[22:25]
	s_setprio 0
	s_setprio 1
	v_mfma_f32_16x16x32_bf16 v[18:21], v[146:149], v[162:165], v[18:21]
	v_mfma_f32_16x16x32_bf16 v[14:17], v[154:157], v[162:165], v[14:17]
	v_mfma_f32_16x16x32_bf16 v[10:13], v[146:149], v[166:169], v[10:13]
	v_mfma_f32_16x16x32_bf16 v[6:9], v[154:157], v[166:169], v[6:9]
	v_mfma_f32_16x16x32_bf16 v[2:5], v[146:149], v[178:181], v[2:5]
	v_mfma_f32_16x16x32_bf16 v[126:129], v[154:157], v[178:181], v[126:129]
	v_mfma_f32_16x16x32_bf16 v[122:125], v[146:149], v[182:185], v[122:125]
	v_mfma_f32_16x16x32_bf16 v[118:121], v[154:157], v[182:185], v[118:121]
	v_mfma_f32_16x16x32_bf16 v[18:21], v[150:153], v[170:173], v[18:21]
	v_mfma_f32_16x16x32_bf16 v[14:17], v[158:161], v[170:173], v[14:17]
	v_mfma_f32_16x16x32_bf16 v[10:13], v[150:153], v[174:177], v[10:13]
	v_mfma_f32_16x16x32_bf16 v[6:9], v[158:161], v[174:177], v[6:9]
	v_mfma_f32_16x16x32_bf16 v[2:5], v[150:153], v[186:189], v[2:5]
	v_mfma_f32_16x16x32_bf16 v[126:129], v[158:161], v[186:189], v[126:129]
	v_mfma_f32_16x16x32_bf16 v[122:125], v[150:153], v[190:193], v[122:125]
	v_mfma_f32_16x16x32_bf16 v[118:121], v[158:161], v[190:193], v[118:121]
	s_setprio 0
	s_barrier
	s_add_i32 s58, s58, 2
	s_addk_i32 s33, 0x100
	s_addk_i32 s57, 0x100
	s_cmp_gt_u32 s58, 13
	s_cbranch_scc0 .LBB0_233
.LBB0_236:
	s_add_i32 s98, s18, 0x2080
	v_mov_b32_e32 v172, v1
	v_mov_b32_e32 v224, v227
	s_lshl_b32 s4, s56, 8
	s_lshl_b32 s18, s55, 8
	s_add_i32 s4, s4, s39
	v_lshlrev_b32_e32 v132, 3, v224
	s_or_b32 s18, s18, s37
	v_lshl_add_u32 v225, v172, 3, s4
	s_add_i32 s4, s55, -2
	v_add_u32_e32 v130, s18, v132
	s_cmp_lt_u32 s4, 16
	s_mov_b64 s[18:19], -1
	v_ashrrev_i32_e32 v131, 31, v130
	s_cbranch_scc1 .LBB0_239
	s_mov_b32 s99, s4
	s_mov_b32 s4, s70
	s_mov_b32 m0, s38
	s_nop 0
	buffer_load_dwordx4 v207, s[4:7], s98 offen lds
	s_mov_b32 m0, s41
	s_nop 0
	buffer_load_dwordx4 v209, s[4:7], s98 offen lds
	s_mov_b32 s4, s99
	v_lshl_add_u64 v[134:135], v[130:131], 2, s[12:13]
	global_load_dwordx4 v[138:141], v[134:135], off
	global_load_dwordx4 v[142:145], v[134:135], off offset:16
	v_ashrrev_i32_e32 v146, 4, v130
	v_and_b32_e32 v136, 8, v132
	v_ashrrev_i32_e32 v132, 4, v225
	v_ashrrev_i32_e32 v147, 31, v146
	v_ashrrev_i32_e32 v133, 31, v132
	v_lshlrev_b64 v[146:147], 12, v[146:147]
	v_mov_b64_e32 v[134:135], s[72:73]
	v_lshlrev_b32_e32 v148, 8, v172
	v_lshl_add_u64 v[146:147], v[146:147], 0, v[132:133]
	v_and_b32_e32 v194, 0x100, v148
	v_mad_u64_u32 v[148:149], s[18:19], v146, s50, v[134:135]
	v_mad_i32_i24 v149, v147, s50, v149
	v_mov_b32_e32 v137, v195
	v_lshlrev_b32_e32 v136, 1, v136
	v_lshl_add_u64 v[146:147], v[148:149], 0, v[194:195]
	v_lshl_add_u64 v[146:147], v[146:147], 0, v[136:137]
	s_waitcnt vmcnt(1)
	v_pk_add_f32 v[148:149], v[116:117], v[140:141]
	v_pk_add_f32 v[150:151], v[114:115], v[138:139]
	s_waitcnt vmcnt(0)
	v_pk_add_f32 v[152:153], v[112:113], v[144:145]
	v_pk_add_f32 v[154:155], v[110:111], v[142:143]
	v_pk_add_f32 v[156:157], v[108:109], v[140:141]
	v_pk_add_f32 v[158:159], v[106:107], v[138:139]
	v_pk_add_f32 v[164:165], v[100:101], v[140:141]
	v_pk_add_f32 v[166:167], v[98:99], v[138:139]
	v_pk_add_f32 v[174:175], v[92:93], v[140:141]
	v_pk_add_f32 v[176:177], v[90:91], v[138:139]
	v_pk_add_f32 v[182:183], v[80:81], v[140:141]
	v_pk_add_f32 v[184:185], v[78:79], v[138:139]
	v_pk_add_f32 v[190:191], v[44:45], v[140:141]
	v_pk_add_f32 v[192:193], v[42:43], v[138:139]
	v_pk_add_f32 v[234:235], v[36:37], v[140:141]
	v_pk_add_f32 v[236:237], v[34:35], v[138:139]
	v_pk_add_f32 v[242:243], v[28:29], v[140:141]
	v_pk_add_f32 v[244:245], v[26:27], v[138:139]
	v_cvt_pk_bf16_f32 v138, v150, v151
	v_cvt_pk_bf16_f32 v139, v148, v149
	v_cvt_pk_bf16_f32 v140, v154, v155
	v_cvt_pk_bf16_f32 v141, v152, v153
	v_pk_add_f32 v[160:161], v[104:105], v[144:145]
	v_pk_add_f32 v[162:163], v[102:103], v[142:143]
	global_store_dwordx4 v[146:147], v[138:141], off
	v_pk_add_f32 v[168:169], v[96:97], v[144:145]
	v_pk_add_f32 v[170:171], v[94:95], v[142:143]
	v_cvt_pk_bf16_f32 v138, v158, v159
	v_cvt_pk_bf16_f32 v139, v156, v157
	v_cvt_pk_bf16_f32 v140, v162, v163
	v_cvt_pk_bf16_f32 v141, v160, v161
	global_store_dwordx4 v[146:147], v[138:141], off offset:32
	v_pk_add_f32 v[178:179], v[88:89], v[144:145]
	v_pk_add_f32 v[180:181], v[86:87], v[142:143]
	v_cvt_pk_bf16_f32 v138, v166, v167
	v_cvt_pk_bf16_f32 v139, v164, v165
	v_cvt_pk_bf16_f32 v140, v170, v171
	v_cvt_pk_bf16_f32 v141, v168, v169
	global_store_dwordx4 v[146:147], v[138:141], off offset:64
	v_pk_add_f32 v[186:187], v[48:49], v[144:145]
	v_pk_add_f32 v[188:189], v[46:47], v[142:143]
	v_cvt_pk_bf16_f32 v138, v176, v177
	v_cvt_pk_bf16_f32 v139, v174, v175
	v_cvt_pk_bf16_f32 v140, v180, v181
	v_cvt_pk_bf16_f32 v141, v178, v179
	global_store_dwordx4 v[146:147], v[138:141], off offset:96
	v_pk_add_f32 v[228:229], v[40:41], v[144:145]
	v_pk_add_f32 v[230:231], v[38:39], v[142:143]
	v_cvt_pk_bf16_f32 v138, v184, v185
	v_cvt_pk_bf16_f32 v139, v182, v183
	v_cvt_pk_bf16_f32 v140, v188, v189
	v_cvt_pk_bf16_f32 v141, v186, v187
	global_store_dwordx4 v[146:147], v[138:141], off offset:128
	v_pk_add_f32 v[238:239], v[32:33], v[144:145]
	v_pk_add_f32 v[240:241], v[30:31], v[142:143]
	v_cvt_pk_bf16_f32 v138, v192, v193
	v_cvt_pk_bf16_f32 v139, v190, v191
	v_cvt_pk_bf16_f32 v140, v230, v231
	v_cvt_pk_bf16_f32 v141, v228, v229
	global_store_dwordx4 v[146:147], v[138:141], off offset:160
	v_pk_add_f32 v[144:145], v[24:25], v[144:145]
	v_pk_add_f32 v[142:143], v[22:23], v[142:143]
	v_cvt_pk_bf16_f32 v138, v236, v237
	v_cvt_pk_bf16_f32 v139, v234, v235
	v_cvt_pk_bf16_f32 v140, v240, v241
	v_cvt_pk_bf16_f32 v141, v238, v239
	global_store_dwordx4 v[146:147], v[138:141], off offset:192
	s_nop 1
	v_cvt_pk_bf16_f32 v138, v244, v245
	v_cvt_pk_bf16_f32 v139, v242, v243
	v_cvt_pk_bf16_f32 v140, v142, v143
	v_cvt_pk_bf16_f32 v141, v144, v145
	global_store_dwordx4 v[146:147], v[138:141], off offset:224
	v_add_u32_e32 v146, 0x80, v130
	v_ashrrev_i32_e32 v147, 31, v146
	v_lshl_add_u64 v[142:143], v[146:147], 2, s[12:13]
	global_load_dwordx4 v[138:141], v[142:143], off
	s_nop 0
	global_load_dwordx4 v[142:145], v[142:143], off offset:16
	v_ashrrev_i32_e32 v146, 4, v146
	v_ashrrev_i32_e32 v147, 31, v146
	v_lshlrev_b64 v[146:147], 12, v[146:147]
	v_lshl_add_u64 v[132:133], v[146:147], 0, v[132:133]
	v_mad_u64_u32 v[134:135], s[18:19], v132, s50, v[134:135]
	v_mad_i32_i24 v135, v133, s50, v135
	v_lshl_add_u64 v[132:133], v[134:135], 0, v[194:195]
	v_lshl_add_u64 v[136:137], v[132:133], 0, v[136:137]
	s_waitcnt vmcnt(1)
	v_pk_add_f32 v[134:135], v[84:85], v[140:141]
	v_pk_add_f32 v[132:133], v[82:83], v[138:139]
	s_waitcnt vmcnt(0)
	v_pk_add_f32 v[146:147], v[76:77], v[144:145]
	v_pk_add_f32 v[148:149], v[74:75], v[142:143]
	v_cvt_pk_bf16_f32 v132, v132, v133
	v_cvt_pk_bf16_f32 v133, v134, v135
	v_pk_add_f32 v[150:151], v[72:73], v[140:141]
	v_cvt_pk_bf16_f32 v134, v148, v149
	v_cvt_pk_bf16_f32 v135, v146, v147
	v_pk_add_f32 v[152:153], v[70:71], v[138:139]
	v_pk_add_f32 v[154:155], v[68:69], v[144:145]
	v_pk_add_f32 v[156:157], v[66:67], v[142:143]
	global_store_dwordx4 v[136:137], v[132:135], off
	v_pk_add_f32 v[158:159], v[64:65], v[140:141]
	v_pk_add_f32 v[160:161], v[62:63], v[138:139]
	v_cvt_pk_bf16_f32 v132, v152, v153
	v_cvt_pk_bf16_f32 v133, v150, v151
	v_cvt_pk_bf16_f32 v134, v156, v157
	v_cvt_pk_bf16_f32 v135, v154, v155
	v_pk_add_f32 v[162:163], v[60:61], v[144:145]
	v_pk_add_f32 v[164:165], v[58:59], v[142:143]
	global_store_dwordx4 v[136:137], v[132:135], off offset:32
	v_pk_add_f32 v[166:167], v[56:57], v[140:141]
	v_pk_add_f32 v[168:169], v[54:55], v[138:139]
	v_cvt_pk_bf16_f32 v132, v160, v161
	v_cvt_pk_bf16_f32 v133, v158, v159
	v_cvt_pk_bf16_f32 v134, v164, v165
	v_cvt_pk_bf16_f32 v135, v162, v163
	v_pk_add_f32 v[170:171], v[52:53], v[144:145]
	v_pk_add_f32 v[174:175], v[50:51], v[142:143]
	global_store_dwordx4 v[136:137], v[132:135], off offset:64
	v_pk_add_f32 v[176:177], v[20:21], v[140:141]
	v_pk_add_f32 v[178:179], v[18:19], v[138:139]
	v_cvt_pk_bf16_f32 v132, v168, v169
	v_cvt_pk_bf16_f32 v133, v166, v167
	v_cvt_pk_bf16_f32 v134, v174, v175
	v_cvt_pk_bf16_f32 v135, v170, v171
	v_pk_add_f32 v[180:181], v[16:17], v[144:145]
	v_pk_add_f32 v[182:183], v[14:15], v[142:143]
	global_store_dwordx4 v[136:137], v[132:135], off offset:96
	v_pk_add_f32 v[184:185], v[12:13], v[140:141]
	v_pk_add_f32 v[186:187], v[10:11], v[138:139]
	v_cvt_pk_bf16_f32 v132, v178, v179
	v_cvt_pk_bf16_f32 v133, v176, v177
	v_cvt_pk_bf16_f32 v134, v182, v183
	v_cvt_pk_bf16_f32 v135, v180, v181
	v_pk_add_f32 v[188:189], v[8:9], v[144:145]
	v_pk_add_f32 v[190:191], v[6:7], v[142:143]
	global_store_dwordx4 v[136:137], v[132:135], off offset:128
	v_pk_add_f32 v[192:193], v[4:5], v[140:141]
	v_pk_add_f32 v[228:229], v[2:3], v[138:139]
	v_cvt_pk_bf16_f32 v132, v186, v187
	v_cvt_pk_bf16_f32 v133, v184, v185
	v_cvt_pk_bf16_f32 v134, v190, v191
	v_cvt_pk_bf16_f32 v135, v188, v189
	v_pk_add_f32 v[230:231], v[128:129], v[144:145]
	v_pk_add_f32 v[234:235], v[126:127], v[142:143]
	global_store_dwordx4 v[136:137], v[132:135], off offset:160
	v_pk_add_f32 v[140:141], v[124:125], v[140:141]
	v_pk_add_f32 v[138:139], v[122:123], v[138:139]
	v_cvt_pk_bf16_f32 v132, v228, v229
	v_cvt_pk_bf16_f32 v133, v192, v193
	v_cvt_pk_bf16_f32 v134, v234, v235
	v_cvt_pk_bf16_f32 v135, v230, v231
	v_pk_add_f32 v[144:145], v[120:121], v[144:145]
	v_pk_add_f32 v[142:143], v[118:119], v[142:143]
	global_store_dwordx4 v[136:137], v[132:135], off offset:192
	s_nop 1
	v_cvt_pk_bf16_f32 v132, v138, v139
	v_cvt_pk_bf16_f32 v133, v140, v141
	v_cvt_pk_bf16_f32 v134, v142, v143
	v_cvt_pk_bf16_f32 v135, v144, v145
	global_store_dwordx4 v[136:137], v[132:135], off offset:224
	s_cbranch_execz .LBB0_240

.LBB0_246:
	s_or_b64 exec, exec, s[18:19]
	s_waitcnt vmcnt(6)
	v_pk_add_f32 v[174:175], v[74:75], v[130:131]
	v_pk_add_f32 v[176:177], v[76:77], v[132:133]
	v_exp_f32_e32 v174, v174
	v_exp_f32_e32 v175, v175
	v_exp_f32_e32 v176, v176
	v_pk_add_f32 v[180:181], v[94:95], v[162:163]
	v_fmamk_f32 v174, v174, 0x3b808081, v223
	v_rcp_f32_e32 v174, v174
	v_fmamk_f32 v175, v175, 0x3b808081, v223
	v_rcp_f32_e32 v175, v175
	v_fmamk_f32 v176, v176, 0x3b808081, v223
	v_rcp_f32_e32 v176, v176
	v_pk_add_f32 v[184:185], v[62:63], v[166:167]
	v_rndne_f32_e32 v174, v174
	v_pk_mul_f32 v[230:231], v[180:181], v[184:185]
	v_pk_add_f32 v[180:181], v[86:87], v[162:163]
	v_pk_add_f32 v[184:185], v[54:55], v[166:167]
	v_cvt_pk_u8_f32 v174, v174, 0, 0
	v_rndne_f32_e32 v175, v175
	v_pk_add_f32 v[178:179], v[96:97], v[164:165]
	v_pk_add_f32 v[182:183], v[64:65], v[168:169]
	v_pk_mul_f32 v[184:185], v[180:181], v[184:185]
	v_pk_add_f32 v[180:181], v[46:47], v[162:163]
	v_pk_add_f32 v[236:237], v[18:19], v[166:167]
	v_pk_add_f32 v[162:163], v[38:39], v[162:163]
	v_pk_add_f32 v[166:167], v[10:11], v[166:167]
	v_cvt_pk_u8_f32 v174, v175, 1, v174
	v_rndne_f32_e32 v175, v176
	v_and_or_b32 v176, v224, 1, v225
	v_pk_mul_f32 v[224:225], v[178:179], v[182:183]
	v_pk_add_f32 v[178:179], v[88:89], v[164:165]
	v_pk_add_f32 v[182:183], v[56:57], v[168:169]
	v_pk_mul_f32 v[166:167], v[162:163], v[166:167]
	v_pk_add_f32 v[162:163], v[66:67], v[130:131]
	v_pk_mul_f32 v[182:183], v[178:179], v[182:183]
	v_pk_add_f32 v[178:179], v[48:49], v[164:165]
	v_pk_add_f32 v[234:235], v[20:21], v[168:169]
	v_pk_add_f32 v[164:165], v[40:41], v[164:165]
	v_pk_add_f32 v[168:169], v[12:13], v[168:169]
	v_exp_f32_e32 v162, v162
	v_exp_f32_e32 v177, v177
	v_pk_mul_f32 v[164:165], v[164:165], v[168:169]
	v_pk_add_f32 v[168:169], v[68:69], v[132:133]
	v_exp_f32_e32 v163, v163
	v_exp_f32_e32 v168, v168
	v_exp_f32_e32 v169, v169
	v_fmamk_f32 v162, v162, 0x3b808081, v223
	v_fmamk_f32 v177, v177, 0x3b808081, v223
	v_rcp_f32_e32 v162, v162
	v_fmamk_f32 v163, v163, 0x3b808081, v223
	v_rcp_f32_e32 v177, v177
	v_rcp_f32_e32 v163, v163
	v_fmamk_f32 v168, v168, 0x3b808081, v223
	v_rcp_f32_e32 v168, v168
	v_fmamk_f32 v169, v169, 0x3b808081, v223
	v_rcp_f32_e32 v169, v169
	v_rndne_f32_e32 v162, v162
	v_cvt_pk_u8_f32 v174, v175, 2, v174
	v_rndne_f32_e32 v175, v177
	v_cvt_pk_u8_f32 v162, v162, 0, 0
	v_rndne_f32_e32 v163, v163
	v_cvt_pk_u8_f32 v228, v175, 3, v174
	v_and_b32_e32 v174, -8, v194
	v_cvt_pk_u8_f32 v162, v163, 1, v162
	v_rndne_f32_e32 v163, v168
	v_add_u32_e32 v174, s33, v174
	v_cvt_pk_u8_f32 v162, v163, 2, v162
	v_rndne_f32_e32 v163, v169
	v_ashrrev_i32_e32 v177, 31, v176
	v_ashrrev_i32_e32 v175, 31, v174
	v_cvt_pk_u8_f32 v229, v163, 3, v162
	v_lshlrev_b64 v[168:169], 10, v[176:177]
	v_lshlrev_b64 v[162:163], 11, v[176:177]
	v_pk_mul_f32 v[178:179], v[178:179], v[234:235]
	v_lshl_add_u64 v[234:235], s[78:79], 0, v[162:163]
	v_lshlrev_b64 v[162:163], 1, v[174:175]
	v_lshl_add_u64 v[168:169], s[76:77], 0, v[168:169]
	v_permlane16_swap_b32_e32 v170, v172
	v_permlane16_swap_b32_e32 v171, v173
	v_permlane16_swap_b32_e32 v228, v229
	v_lshl_add_u64 v[234:235], v[234:235], 0, v[162:163]
	v_lshl_add_u64 v[168:169], v[168:169], 0, v[174:175]
	global_store_dwordx4 v[234:235], v[170:173], off
	global_store_dwordx2 v[168:169], v[228:229], off
	v_pk_fma_f32 v[228:229], v[230:231], v[146:147], v[150:151]
	v_pk_fma_f32 v[172:173], v[224:225], v[148:149], v[152:153]
	v_pk_fma_f32 v[228:229], v[142:143], v[192:193], v[228:229]
	v_pk_fma_f32 v[172:173], v[144:145], v[190:191], v[172:173]
	v_pk_add_f32 v[168:169], v[100:101], v[140:141]
	v_pk_add_f32 v[170:171], v[98:99], v[138:139]
	v_pk_fma_f32 v[172:173], v[136:137], v[186:187], v[172:173]
	v_pk_fma_f32 v[186:187], v[134:135], v[188:189], v[228:229]
	v_pk_mul_f32 v[172:173], v[168:169], v[172:173]
	v_pk_mul_f32 v[168:169], v[170:171], v[186:187]
	v_pk_add_f32 v[170:171], v[58:59], v[130:131]
	v_cvt_pk_bf16_f32 v168, v168, v169
	v_cvt_pk_bf16_f32 v169, v172, v173
	v_pk_add_f32 v[172:173], v[60:61], v[132:133]
	v_exp_f32_e32 v170, v170
	v_exp_f32_e32 v171, v171
	v_exp_f32_e32 v172, v172
	v_exp_f32_e32 v173, v173
	v_fmamk_f32 v170, v170, 0x3b808081, v223
	v_rcp_f32_e32 v170, v170
	v_fmamk_f32 v171, v171, 0x3b808081, v223
	v_rcp_f32_e32 v171, v171
	v_fmamk_f32 v172, v172, 0x3b808081, v223
	v_rcp_f32_e32 v172, v172
	v_fmamk_f32 v173, v173, 0x3b808081, v223
	v_rcp_f32_e32 v173, v173
	v_rndne_f32_e32 v170, v170
	v_cvt_pk_u8_f32 v170, v170, 0, 0
	v_rndne_f32_e32 v171, v171
	v_cvt_pk_u8_f32 v170, v171, 1, v170
	v_rndne_f32_e32 v171, v172
	v_pk_fma_f32 v[188:189], v[182:183], v[148:149], v[152:153]
	v_pk_fma_f32 v[228:229], v[184:185], v[146:147], v[150:151]
	v_cvt_pk_u8_f32 v170, v171, 2, v170
	v_rndne_f32_e32 v171, v173
	v_pk_fma_f32 v[188:189], v[144:145], v[224:225], v[188:189]
	v_pk_fma_f32 v[228:229], v[142:143], v[230:231], v[228:229]
	v_cvt_pk_u8_f32 v172, v171, 3, v170
	v_pk_add_f32 v[170:171], v[92:93], v[140:141]
	v_pk_add_f32 v[186:187], v[90:91], v[138:139]
	v_pk_fma_f32 v[188:189], v[136:137], v[190:191], v[188:189]
	v_pk_fma_f32 v[190:191], v[134:135], v[192:193], v[228:229]
	v_pk_mul_f32 v[188:189], v[170:171], v[188:189]
	v_pk_mul_f32 v[170:171], v[186:187], v[190:191]
	v_pk_add_f32 v[186:187], v[50:51], v[130:131]
	v_cvt_pk_bf16_f32 v170, v170, v171
	v_cvt_pk_bf16_f32 v171, v188, v189
	v_pk_add_f32 v[188:189], v[52:53], v[132:133]
	v_exp_f32_e32 v173, v186
	v_exp_f32_e32 v177, v187
	v_exp_f32_e32 v186, v188
	v_exp_f32_e32 v187, v189
	v_fmamk_f32 v173, v173, 0x3b808081, v223
	v_rcp_f32_e32 v173, v173
	v_fmamk_f32 v177, v177, 0x3b808081, v223
	v_rcp_f32_e32 v177, v177
	v_fmamk_f32 v186, v186, 0x3b808081, v223
	v_rcp_f32_e32 v186, v186
	v_fmamk_f32 v187, v187, 0x3b808081, v223
	v_rcp_f32_e32 v187, v187
	v_rndne_f32_e32 v173, v173
	v_cvt_pk_u8_f32 v173, v173, 0, 0
	v_rndne_f32_e32 v177, v177
	v_cvt_pk_u8_f32 v173, v177, 1, v173
	v_rndne_f32_e32 v177, v186
	v_or_b32_e32 v186, 2, v176
	v_cvt_pk_u8_f32 v173, v177, 2, v173
	v_rndne_f32_e32 v177, v187
	v_ashrrev_i32_e32 v187, 31, v186
	v_lshlrev_b64 v[188:189], 10, v[186:187]
	v_lshlrev_b64 v[186:187], 11, v[186:187]
	v_lshl_add_u64 v[186:187], s[78:79], 0, v[186:187]
	v_pk_mul_f32 v[180:181], v[180:181], v[236:237]
	v_permlane16_swap_b32_e32 v168, v170
	v_permlane16_swap_b32_e32 v169, v171
	v_lshl_add_u64 v[186:187], v[186:187], 0, v[162:163]
	v_cvt_pk_u8_f32 v173, v177, 3, v173
	global_store_dwordx4 v[186:187], v[168:171], off
	v_pk_fma_f32 v[186:187], v[178:179], v[148:149], v[152:153]
	v_permlane16_swap_b32_e32 v172, v173
	v_lshl_add_u64 v[168:169], s[76:77], 0, v[188:189]
	v_pk_fma_f32 v[188:189], v[180:181], v[146:147], v[150:151]
	v_lshl_add_u64 v[168:169], v[168:169], 0, v[174:175]
	v_pk_fma_f32 v[186:187], v[144:145], v[182:183], v[186:187]
	v_pk_fma_f32 v[188:189], v[142:143], v[184:185], v[188:189]
	global_store_dwordx2 v[168:169], v[172:173], off
	v_pk_add_f32 v[168:169], v[80:81], v[140:141]
	v_pk_add_f32 v[170:171], v[78:79], v[138:139]
	v_pk_fma_f32 v[186:187], v[136:137], v[224:225], v[186:187]
	v_pk_fma_f32 v[188:189], v[134:135], v[230:231], v[188:189]
	v_pk_mul_f32 v[186:187], v[168:169], v[186:187]
	v_pk_mul_f32 v[168:169], v[170:171], v[188:189]
	v_pk_add_f32 v[170:171], v[14:15], v[130:131]
	v_cvt_pk_bf16_f32 v168, v168, v169
	v_cvt_pk_bf16_f32 v169, v186, v187
	v_pk_add_f32 v[186:187], v[16:17], v[132:133]
	v_exp_f32_e32 v170, v170
	v_exp_f32_e32 v171, v171
	v_exp_f32_e32 v173, v186
	v_exp_f32_e32 v177, v187
	v_fmamk_f32 v170, v170, 0x3b808081, v223
	v_rcp_f32_e32 v170, v170
	v_fmamk_f32 v171, v171, 0x3b808081, v223
	v_rcp_f32_e32 v171, v171
	v_fmamk_f32 v173, v173, 0x3b808081, v223
	v_rcp_f32_e32 v173, v173
	v_fmamk_f32 v177, v177, 0x3b808081, v223
	v_rcp_f32_e32 v177, v177
	v_rndne_f32_e32 v170, v170
	v_cvt_pk_u8_f32 v170, v170, 0, 0
	v_rndne_f32_e32 v171, v171
	v_cvt_pk_u8_f32 v170, v171, 1, v170
	v_rndne_f32_e32 v171, v173
	v_pk_fma_f32 v[190:191], v[164:165], v[148:149], v[152:153]
	v_pk_fma_f32 v[192:193], v[166:167], v[146:147], v[150:151]
	v_cvt_pk_u8_f32 v170, v171, 2, v170
	v_rndne_f32_e32 v171, v177
	v_pk_fma_f32 v[190:191], v[144:145], v[178:179], v[190:191]
	v_pk_fma_f32 v[192:193], v[142:143], v[180:181], v[192:193]
	v_cvt_pk_u8_f32 v186, v171, 3, v170
	v_pk_add_f32 v[170:171], v[44:45], v[140:141]
	v_pk_add_f32 v[188:189], v[42:43], v[138:139]
	v_pk_fma_f32 v[182:183], v[136:137], v[182:183], v[190:191]
	v_pk_fma_f32 v[184:185], v[134:135], v[184:185], v[192:193]
	v_pk_mul_f32 v[182:183], v[170:171], v[182:183]
	v_pk_mul_f32 v[170:171], v[188:189], v[184:185]
	v_pk_add_f32 v[184:185], v[8:9], v[132:133]
	v_cvt_pk_bf16_f32 v170, v170, v171
	v_cvt_pk_bf16_f32 v171, v182, v183
	v_pk_add_f32 v[182:183], v[6:7], v[130:131]
	v_or_b32_e32 v172, 4, v176
	v_exp_f32_e32 v173, v182
	v_exp_f32_e32 v177, v183
	v_exp_f32_e32 v182, v184
	v_exp_f32_e32 v183, v185
	v_fmamk_f32 v173, v173, 0x3b808081, v223
	v_rcp_f32_e32 v173, v173
	v_fmamk_f32 v177, v177, 0x3b808081, v223
	v_rcp_f32_e32 v177, v177
	v_fmamk_f32 v182, v182, 0x3b808081, v223
	v_rcp_f32_e32 v182, v182
	v_fmamk_f32 v183, v183, 0x3b808081, v223
	v_rcp_f32_e32 v183, v183
	v_rndne_f32_e32 v173, v173
	v_cvt_pk_u8_f32 v173, v173, 0, 0
	v_rndne_f32_e32 v177, v177
	v_cvt_pk_u8_f32 v173, v177, 1, v173
	v_rndne_f32_e32 v177, v182
	v_cvt_pk_u8_f32 v173, v177, 2, v173
	v_rndne_f32_e32 v177, v183
	v_cvt_pk_u8_f32 v187, v177, 3, v173
	v_ashrrev_i32_e32 v173, 31, v172
	v_lshlrev_b64 v[182:183], 10, v[172:173]
	v_lshlrev_b64 v[172:173], 11, v[172:173]
	v_lshl_add_u64 v[172:173], s[78:79], 0, v[172:173]
	v_permlane16_swap_b32_e32 v168, v170
	v_permlane16_swap_b32_e32 v169, v171
	v_lshl_add_u64 v[172:173], v[172:173], 0, v[162:163]
	global_store_dwordx4 v[172:173], v[168:171], off
	v_pk_fma_f32 v[172:173], v[156:157], v[148:149], v[152:153]
	v_permlane16_swap_b32_e32 v186, v187
	v_lshl_add_u64 v[168:169], s[76:77], 0, v[182:183]
	v_pk_fma_f32 v[182:183], v[154:155], v[146:147], v[150:151]
	v_lshl_add_u64 v[168:169], v[168:169], 0, v[174:175]
	v_pk_fma_f32 v[172:173], v[144:145], v[164:165], v[172:173]
	v_pk_fma_f32 v[182:183], v[142:143], v[166:167], v[182:183]
	global_store_dwordx2 v[168:169], v[186:187], off
	v_pk_add_f32 v[168:169], v[36:37], v[140:141]
	v_pk_add_f32 v[170:171], v[34:35], v[138:139]
	v_pk_fma_f32 v[172:173], v[136:137], v[178:179], v[172:173]
	v_pk_fma_f32 v[178:179], v[134:135], v[180:181], v[182:183]
	v_pk_mul_f32 v[172:173], v[168:169], v[172:173]
	v_pk_mul_f32 v[168:169], v[170:171], v[178:179]
	v_pk_add_f32 v[170:171], v[126:127], v[130:131]
	v_pk_add_f32 v[130:131], v[118:119], v[130:131]
	v_cvt_pk_bf16_f32 v168, v168, v169
	v_cvt_pk_bf16_f32 v169, v172, v173
	v_exp_f32_e32 v170, v170
	v_exp_f32_e32 v130, v130
	v_pk_add_f32 v[172:173], v[128:129], v[132:133]
	v_pk_add_f32 v[132:133], v[120:121], v[132:133]
	v_exp_f32_e32 v131, v131
	v_exp_f32_e32 v171, v171
	v_exp_f32_e32 v132, v132
	v_exp_f32_e32 v172, v172
	v_exp_f32_e32 v133, v133
	v_exp_f32_e32 v173, v173
	v_fmamk_f32 v130, v130, 0x3b808081, v223
	v_fmamk_f32 v170, v170, 0x3b808081, v223
	v_rcp_f32_e32 v130, v130
	v_fmamk_f32 v131, v131, 0x3b808081, v223
	v_rcp_f32_e32 v170, v170
	v_fmamk_f32 v171, v171, 0x3b808081, v223
	v_rcp_f32_e32 v131, v131
	v_fmamk_f32 v132, v132, 0x3b808081, v223
	v_rcp_f32_e32 v171, v171
	v_fmamk_f32 v172, v172, 0x3b808081, v223
	v_rcp_f32_e32 v132, v132
	v_fmamk_f32 v133, v133, 0x3b808081, v223
	v_rcp_f32_e32 v172, v172
	v_fmamk_f32 v173, v173, 0x3b808081, v223
	v_rcp_f32_e32 v133, v133
	v_rcp_f32_e32 v173, v173
	v_rndne_f32_e32 v130, v130
	v_rndne_f32_e32 v170, v170
	v_cvt_pk_u8_f32 v130, v130, 0, 0
	v_rndne_f32_e32 v131, v131
	v_cvt_pk_u8_f32 v170, v170, 0, 0
	v_rndne_f32_e32 v171, v171
	v_cvt_pk_u8_f32 v130, v131, 1, v130
	v_rndne_f32_e32 v131, v132
	v_cvt_pk_u8_f32 v170, v171, 1, v170
	v_rndne_f32_e32 v171, v172
	v_cvt_pk_u8_f32 v130, v131, 2, v130
	v_rndne_f32_e32 v131, v133
	v_cvt_pk_u8_f32 v170, v171, 2, v170
	v_rndne_f32_e32 v171, v173
	v_pk_fma_f32 v[148:149], v[160:161], v[148:149], v[152:153]
	v_pk_fma_f32 v[146:147], v[158:159], v[146:147], v[150:151]
	v_cvt_pk_u8_f32 v173, v131, 3, v130
	v_or_b32_e32 v130, 6, v176
	v_pk_fma_f32 v[144:145], v[144:145], v[156:157], v[148:149]
	v_pk_fma_f32 v[142:143], v[142:143], v[154:155], v[146:147]
	v_ashrrev_i32_e32 v131, 31, v130
	v_pk_add_f32 v[140:141], v[28:29], v[140:141]
	v_pk_add_f32 v[138:139], v[26:27], v[138:139]
	v_pk_fma_f32 v[136:137], v[136:137], v[164:165], v[144:145]
	v_pk_fma_f32 v[134:135], v[134:135], v[166:167], v[142:143]
	v_lshlrev_b64 v[132:133], 10, v[130:131]
	v_lshlrev_b64 v[130:131], 11, v[130:131]
	v_cvt_pk_u8_f32 v172, v171, 3, v170
	v_pk_mul_f32 v[136:137], v[140:141], v[136:137]
	v_pk_mul_f32 v[134:135], v[138:139], v[134:135]
	v_lshl_add_u64 v[130:131], s[78:79], 0, v[130:131]
	v_cvt_pk_bf16_f32 v170, v134, v135
	v_cvt_pk_bf16_f32 v171, v136, v137
	v_lshl_add_u64 v[130:131], v[130:131], 0, v[162:163]
	v_permlane16_swap_b32_e32 v168, v170
	v_permlane16_swap_b32_e32 v169, v171
	global_store_dwordx4 v[130:131], v[168:171], off
	v_lshl_add_u64 v[130:131], s[76:77], 0, v[132:133]
	v_permlane16_swap_b32_e32 v172, v173
	v_lshl_add_u64 v[130:131], v[130:131], 0, v[174:175]
	global_store_dwordx2 v[130:131], v[172:173], off
	s_andn2_b64 vcc, exec, s[2:3]
	s_mov_b64 s[2:3], -1
	s_cbranch_vccnz .LBB0_217
.LBB0_247:
	s_branch .LBB0_216

.LBB0_253:
	s_cmp_lg_u64 s[16:17], 0
	s_cbranch_scc0 my_skew_p1
	s_barrier
my_skew_p1:
	s_waitcnt vmcnt(0)
	v_readlane_b32 s58, v252, 3
	v_readlane_b32 s59, v252, 4
	s_barrier

.LBB0_1122:
	ds_read_b128 v[130:133], v240
	ds_read_b128 v[134:137], v241
	ds_read_b128 v[138:141], v242
	ds_read_b128 v[142:145], v243
	ds_read_b128 v[146:149], v244
	ds_read_b128 v[150:153], v245
	ds_read_b128 v[154:157], v246
	ds_read_b128 v[158:161], v247
	s_add_i32 s8, s31, s53
	s_add_i32 s55, s26, s53
	s_add_i32 s54, s8, 0x800
	s_addk_i32 s55, 0x800
	s_cmp_eq_u32 s53, 0
	s_cselect_b32 s56, s4, s54
	s_cselect_b32 s55, s5, s55
	s_add_i32 s54, s56, 0x80
	s_add_i32 s57, s8, 0x40780
	s_mov_b32 s8, s70
	s_mov_b32 m0, s44
	ds_read_b128 v[162:165], v248
	ds_read_b128 v[166:169], v248 offset:2048
	ds_read_b128 v[170:173], v249
	ds_read_b128 v[174:177], v249 offset:2048
	ds_read_b128 v[178:181], v248 offset:4096
	ds_read_b128 v[182:185], v248 offset:6144
	ds_read_b128 v[186:189], v249 offset:4096
	ds_read_b128 v[190:193], v249 offset:6144
	buffer_load_dwordx4 v1, s[8:11], s57 offen lds
	s_mov_b32 m0, s45
	s_nop 0
	buffer_load_dwordx4 v234, s[8:11], s57 offen lds
	s_waitcnt vmcnt(8)
	s_waitcnt lgkmcnt(0)
	s_barrier
	s_setprio 1
	s_waitcnt lgkmcnt(7)
	v_mfma_f32_16x16x32_bf16 v[126:129], v[130:133], v[162:165], v[126:129]
	v_mfma_f32_16x16x32_bf16 v[122:125], v[138:141], v[162:165], v[122:125]
	s_waitcnt lgkmcnt(6)
	v_mfma_f32_16x16x32_bf16 v[118:121], v[130:133], v[166:169], v[118:121]
	v_mfma_f32_16x16x32_bf16 v[114:117], v[138:141], v[166:169], v[114:117]
	s_waitcnt lgkmcnt(3)
	v_mfma_f32_16x16x32_bf16 v[110:113], v[130:133], v[178:181], v[110:113]
	v_mfma_f32_16x16x32_bf16 v[106:109], v[138:141], v[178:181], v[106:109]
	s_waitcnt lgkmcnt(2)
	v_mfma_f32_16x16x32_bf16 v[102:105], v[130:133], v[182:185], v[102:105]
	v_mfma_f32_16x16x32_bf16 v[98:101], v[138:141], v[182:185], v[98:101]
	v_mfma_f32_16x16x32_bf16 v[126:129], v[134:137], v[170:173], v[126:129]
	v_mfma_f32_16x16x32_bf16 v[122:125], v[142:145], v[170:173], v[122:125]
	v_mfma_f32_16x16x32_bf16 v[118:121], v[134:137], v[174:177], v[118:121]
	v_mfma_f32_16x16x32_bf16 v[114:117], v[142:145], v[174:177], v[114:117]
	s_waitcnt lgkmcnt(1)
	v_mfma_f32_16x16x32_bf16 v[110:113], v[134:137], v[186:189], v[110:113]
	v_mfma_f32_16x16x32_bf16 v[106:109], v[142:145], v[186:189], v[106:109]
	s_waitcnt lgkmcnt(0)
	v_mfma_f32_16x16x32_bf16 v[102:105], v[134:137], v[190:193], v[102:105]
	v_mfma_f32_16x16x32_bf16 v[98:101], v[142:145], v[190:193], v[98:101]
	s_setprio 0
	s_setprio 1
	v_mfma_f32_16x16x32_bf16 v[94:97], v[146:149], v[162:165], v[94:97]
	v_mfma_f32_16x16x32_bf16 v[90:93], v[154:157], v[162:165], v[90:93]
	v_mfma_f32_16x16x32_bf16 v[86:89], v[146:149], v[166:169], v[86:89]
	v_mfma_f32_16x16x32_bf16 v[82:85], v[154:157], v[166:169], v[82:85]
	v_mfma_f32_16x16x32_bf16 v[78:81], v[146:149], v[178:181], v[78:81]
	v_mfma_f32_16x16x32_bf16 v[74:77], v[154:157], v[178:181], v[74:77]
	v_mfma_f32_16x16x32_bf16 v[70:73], v[146:149], v[182:185], v[70:73]
	v_mfma_f32_16x16x32_bf16 v[66:69], v[154:157], v[182:185], v[66:69]
	v_mfma_f32_16x16x32_bf16 v[94:97], v[150:153], v[170:173], v[94:97]
	v_mfma_f32_16x16x32_bf16 v[90:93], v[158:161], v[170:173], v[90:93]
	v_mfma_f32_16x16x32_bf16 v[86:89], v[150:153], v[174:177], v[86:89]
	v_mfma_f32_16x16x32_bf16 v[82:85], v[158:161], v[174:177], v[82:85]
	v_mfma_f32_16x16x32_bf16 v[78:81], v[150:153], v[186:189], v[78:81]
	v_mfma_f32_16x16x32_bf16 v[74:77], v[158:161], v[186:189], v[74:77]
	v_mfma_f32_16x16x32_bf16 v[70:73], v[150:153], v[190:193], v[70:73]
	v_mfma_f32_16x16x32_bf16 v[66:69], v[158:161], v[190:193], v[66:69]
	s_setprio 0
	s_barrier
	s_mov_b32 m0, s23
	ds_read_b128 v[162:165], v248 offset:16384
	ds_read_b128 v[166:169], v248 offset:18432
	ds_read_b128 v[170:173], v249 offset:16384
	ds_read_b128 v[174:177], v249 offset:18432
	ds_read_b128 v[178:181], v248 offset:20480
	ds_read_b128 v[182:185], v248 offset:22528
	ds_read_b128 v[186:189], v249 offset:20480
	ds_read_b128 v[190:193], v249 offset:22528
	buffer_load_dwordx4 v233, s[8:11], s55 offen lds
	s_mov_b32 m0, s24
	s_add_i32 s57, s55, 0x40000
	buffer_load_dwordx4 v235, s[8:11], s55 offen lds
	s_mov_b32 m0, s25
	s_nop 0
	buffer_load_dwordx4 v233, s[8:11], s57 offen lds
	s_mov_b32 m0, s27
	s_nop 0
	buffer_load_dwordx4 v235, s[8:11], s57 offen lds
	s_mov_b32 m0, s22
	s_nop 0
	buffer_load_dwordx4 v1, s[8:11], s56 offen lds
	s_mov_b32 m0, s28
	s_nop 0
	buffer_load_dwordx4 v234, s[8:11], s56 offen lds
	s_waitcnt vmcnt(8)
	s_waitcnt lgkmcnt(0)
	s_barrier
	s_setprio 1
	s_waitcnt lgkmcnt(7)
	v_mfma_f32_16x16x32_bf16 v[62:65], v[130:133], v[162:165], v[62:65]
	v_mfma_f32_16x16x32_bf16 v[58:61], v[138:141], v[162:165], v[58:61]
	s_waitcnt lgkmcnt(6)
	v_mfma_f32_16x16x32_bf16 v[54:57], v[130:133], v[166:169], v[54:57]
	v_mfma_f32_16x16x32_bf16 v[50:53], v[138:141], v[166:169], v[50:53]
	s_waitcnt lgkmcnt(3)
	v_mfma_f32_16x16x32_bf16 v[46:49], v[130:133], v[178:181], v[46:49]
	v_mfma_f32_16x16x32_bf16 v[42:45], v[138:141], v[178:181], v[42:45]
	s_waitcnt lgkmcnt(2)
	v_mfma_f32_16x16x32_bf16 v[38:41], v[130:133], v[182:185], v[38:41]
	v_mfma_f32_16x16x32_bf16 v[34:37], v[138:141], v[182:185], v[34:37]
	v_mfma_f32_16x16x32_bf16 v[62:65], v[134:137], v[170:173], v[62:65]
	v_mfma_f32_16x16x32_bf16 v[58:61], v[142:145], v[170:173], v[58:61]
	v_mfma_f32_16x16x32_bf16 v[54:57], v[134:137], v[174:177], v[54:57]
	v_mfma_f32_16x16x32_bf16 v[50:53], v[142:145], v[174:177], v[50:53]
	s_waitcnt lgkmcnt(1)
	v_mfma_f32_16x16x32_bf16 v[46:49], v[134:137], v[186:189], v[46:49]
	v_mfma_f32_16x16x32_bf16 v[42:45], v[142:145], v[186:189], v[42:45]
	s_waitcnt lgkmcnt(0)
	v_mfma_f32_16x16x32_bf16 v[38:41], v[134:137], v[190:193], v[38:41]
	v_mfma_f32_16x16x32_bf16 v[34:37], v[142:145], v[190:193], v[34:37]
	s_setprio 0
	s_setprio 1
	v_mfma_f32_16x16x32_bf16 v[30:33], v[146:149], v[162:165], v[30:33]
	v_mfma_f32_16x16x32_bf16 v[26:29], v[154:157], v[162:165], v[26:29]
	v_mfma_f32_16x16x32_bf16 v[22:25], v[146:149], v[166:169], v[22:25]
	v_mfma_f32_16x16x32_bf16 v[18:21], v[154:157], v[166:169], v[18:21]
	v_mfma_f32_16x16x32_bf16 v[14:17], v[146:149], v[178:181], v[14:17]
	v_mfma_f32_16x16x32_bf16 v[10:13], v[154:157], v[178:181], v[10:13]
	v_mfma_f32_16x16x32_bf16 v[6:9], v[146:149], v[182:185], v[6:9]
	v_mfma_f32_16x16x32_bf16 v[2:5], v[154:157], v[182:185], v[2:5]
	v_mfma_f32_16x16x32_bf16 v[30:33], v[150:153], v[170:173], v[30:33]
	v_mfma_f32_16x16x32_bf16 v[26:29], v[158:161], v[170:173], v[26:29]
	v_mfma_f32_16x16x32_bf16 v[22:25], v[150:153], v[174:177], v[22:25]
	v_mfma_f32_16x16x32_bf16 v[18:21], v[158:161], v[174:177], v[18:21]
	v_mfma_f32_16x16x32_bf16 v[14:17], v[150:153], v[186:189], v[14:17]
	v_mfma_f32_16x16x32_bf16 v[10:13], v[158:161], v[186:189], v[10:13]
	v_mfma_f32_16x16x32_bf16 v[6:9], v[150:153], v[190:193], v[6:9]
	v_mfma_f32_16x16x32_bf16 v[2:5], v[158:161], v[190:193], v[2:5]
	s_setprio 0
	s_barrier
	ds_read_b128 v[130:133], v194
	ds_read_b128 v[134:137], v195
	ds_read_b128 v[138:141], v196
	ds_read_b128 v[142:145], v197
	ds_read_b128 v[146:149], v198
	ds_read_b128 v[150:153], v199
	ds_read_b128 v[154:157], v200
	ds_read_b128 v[158:161], v201
	s_add_i32 s56, s56, 0x40000
	s_mov_b32 m0, s29
	ds_read_b128 v[162:165], v248 offset:32768
	ds_read_b128 v[166:169], v248 offset:34816
	ds_read_b128 v[170:173], v249 offset:32768
	ds_read_b128 v[174:177], v249 offset:34816
	ds_read_b128 v[178:181], v248 offset:36864
	ds_read_b128 v[182:185], v248 offset:38912
	ds_read_b128 v[186:189], v249 offset:36864
	ds_read_b128 v[190:193], v249 offset:38912
	buffer_load_dwordx4 v1, s[8:11], s56 offen lds
	s_mov_b32 m0, s30
	s_nop 0
	buffer_load_dwordx4 v234, s[8:11], s56 offen lds
	s_waitcnt vmcnt(8)
	s_waitcnt lgkmcnt(0)
	s_barrier
	s_setprio 1
	s_waitcnt lgkmcnt(7)
	v_mfma_f32_16x16x32_bf16 v[126:129], v[130:133], v[162:165], v[126:129]
	v_mfma_f32_16x16x32_bf16 v[122:125], v[138:141], v[162:165], v[122:125]
	s_waitcnt lgkmcnt(6)
	v_mfma_f32_16x16x32_bf16 v[118:121], v[130:133], v[166:169], v[118:121]
	v_mfma_f32_16x16x32_bf16 v[114:117], v[138:141], v[166:169], v[114:117]
	s_waitcnt lgkmcnt(3)
	v_mfma_f32_16x16x32_bf16 v[110:113], v[130:133], v[178:181], v[110:113]
	v_mfma_f32_16x16x32_bf16 v[106:109], v[138:141], v[178:181], v[106:109]
	s_waitcnt lgkmcnt(2)
	v_mfma_f32_16x16x32_bf16 v[102:105], v[130:133], v[182:185], v[102:105]
	v_mfma_f32_16x16x32_bf16 v[98:101], v[138:141], v[182:185], v[98:101]
	v_mfma_f32_16x16x32_bf16 v[126:129], v[134:137], v[170:173], v[126:129]
	v_mfma_f32_16x16x32_bf16 v[122:125], v[142:145], v[170:173], v[122:125]
	v_mfma_f32_16x16x32_bf16 v[118:121], v[134:137], v[174:177], v[118:121]
	v_mfma_f32_16x16x32_bf16 v[114:117], v[142:145], v[174:177], v[114:117]
	s_waitcnt lgkmcnt(1)
	v_mfma_f32_16x16x32_bf16 v[110:113], v[134:137], v[186:189], v[110:113]
	v_mfma_f32_16x16x32_bf16 v[106:109], v[142:145], v[186:189], v[106:109]
	s_waitcnt lgkmcnt(0)
	v_mfma_f32_16x16x32_bf16 v[102:105], v[134:137], v[190:193], v[102:105]
	v_mfma_f32_16x16x32_bf16 v[98:101], v[142:145], v[190:193], v[98:101]
	s_setprio 0
	s_setprio 1
	v_mfma_f32_16x16x32_bf16 v[94:97], v[146:149], v[162:165], v[94:97]
	v_mfma_f32_16x16x32_bf16 v[90:93], v[154:157], v[162:165], v[90:93]
	v_mfma_f32_16x16x32_bf16 v[86:89], v[146:149], v[166:169], v[86:89]
	v_mfma_f32_16x16x32_bf16 v[82:85], v[154:157], v[166:169], v[82:85]
	v_mfma_f32_16x16x32_bf16 v[78:81], v[146:149], v[178:181], v[78:81]
	v_mfma_f32_16x16x32_bf16 v[74:77], v[154:157], v[178:181], v[74:77]
	v_mfma_f32_16x16x32_bf16 v[70:73], v[146:149], v[182:185], v[70:73]
	v_mfma_f32_16x16x32_bf16 v[66:69], v[154:157], v[182:185], v[66:69]
	v_mfma_f32_16x16x32_bf16 v[94:97], v[150:153], v[170:173], v[94:97]
	v_mfma_f32_16x16x32_bf16 v[90:93], v[158:161], v[170:173], v[90:93]
	v_mfma_f32_16x16x32_bf16 v[86:89], v[150:153], v[174:177], v[86:89]
	v_mfma_f32_16x16x32_bf16 v[82:85], v[158:161], v[174:177], v[82:85]
	v_mfma_f32_16x16x32_bf16 v[78:81], v[150:153], v[186:189], v[78:81]
	v_mfma_f32_16x16x32_bf16 v[74:77], v[158:161], v[186:189], v[74:77]
	v_mfma_f32_16x16x32_bf16 v[70:73], v[150:153], v[190:193], v[70:73]
	v_mfma_f32_16x16x32_bf16 v[66:69], v[158:161], v[190:193], v[66:69]
	s_setprio 0
	s_barrier
	s_mov_b32 m0, s35
	s_add_i32 s56, s55, 0x80
	ds_read_b128 v[162:165], v248 offset:49152
	ds_read_b128 v[166:169], v248 offset:51200
	ds_read_b128 v[170:173], v249 offset:49152
	ds_read_b128 v[174:177], v249 offset:51200
	ds_read_b128 v[178:181], v248 offset:53248
	ds_read_b128 v[182:185], v248 offset:55296
	ds_read_b128 v[186:189], v249 offset:53248
	ds_read_b128 v[190:193], v249 offset:55296
	buffer_load_dwordx4 v233, s[8:11], s56 offen lds
	s_mov_b32 m0, s36
	s_add_i32 s55, s55, 0x40080
	buffer_load_dwordx4 v235, s[8:11], s56 offen lds
	s_mov_b32 m0, s39
	s_nop 0
	buffer_load_dwordx4 v233, s[8:11], s55 offen lds
	s_mov_b32 m0, s41
	s_nop 0
	buffer_load_dwordx4 v235, s[8:11], s55 offen lds
	s_mov_b32 m0, s37
	s_nop 0
	buffer_load_dwordx4 v1, s[8:11], s54 offen lds
	s_mov_b32 m0, s38
	s_nop 0
	buffer_load_dwordx4 v234, s[8:11], s54 offen lds
	s_waitcnt vmcnt(8)
	s_waitcnt lgkmcnt(0)
	s_barrier
	s_setprio 1
	s_waitcnt lgkmcnt(7)
	v_mfma_f32_16x16x32_bf16 v[62:65], v[130:133], v[162:165], v[62:65]
	v_mfma_f32_16x16x32_bf16 v[58:61], v[138:141], v[162:165], v[58:61]
	s_waitcnt lgkmcnt(6)
	v_mfma_f32_16x16x32_bf16 v[54:57], v[130:133], v[166:169], v[54:57]
	v_mfma_f32_16x16x32_bf16 v[50:53], v[138:141], v[166:169], v[50:53]
	s_waitcnt lgkmcnt(3)
	v_mfma_f32_16x16x32_bf16 v[46:49], v[130:133], v[178:181], v[46:49]
	v_mfma_f32_16x16x32_bf16 v[42:45], v[138:141], v[178:181], v[42:45]
	s_waitcnt lgkmcnt(2)
	v_mfma_f32_16x16x32_bf16 v[38:41], v[130:133], v[182:185], v[38:41]
	v_mfma_f32_16x16x32_bf16 v[34:37], v[138:141], v[182:185], v[34:37]
	v_mfma_f32_16x16x32_bf16 v[62:65], v[134:137], v[170:173], v[62:65]
	v_mfma_f32_16x16x32_bf16 v[58:61], v[142:145], v[170:173], v[58:61]
	v_mfma_f32_16x16x32_bf16 v[54:57], v[134:137], v[174:177], v[54:57]
	v_mfma_f32_16x16x32_bf16 v[50:53], v[142:145], v[174:177], v[50:53]
	s_waitcnt lgkmcnt(1)
	v_mfma_f32_16x16x32_bf16 v[46:49], v[134:137], v[186:189], v[46:49]
	v_mfma_f32_16x16x32_bf16 v[42:45], v[142:145], v[186:189], v[42:45]
	s_waitcnt lgkmcnt(0)
	v_mfma_f32_16x16x32_bf16 v[38:41], v[134:137], v[190:193], v[38:41]
	v_mfma_f32_16x16x32_bf16 v[34:37], v[142:145], v[190:193], v[34:37]
	s_setprio 0
	s_setprio 1
	v_mfma_f32_16x16x32_bf16 v[30:33], v[146:149], v[162:165], v[30:33]
	v_mfma_f32_16x16x32_bf16 v[26:29], v[154:157], v[162:165], v[26:29]
	v_mfma_f32_16x16x32_bf16 v[22:25], v[146:149], v[166:169], v[22:25]
	v_mfma_f32_16x16x32_bf16 v[18:21], v[154:157], v[166:169], v[18:21]
	v_mfma_f32_16x16x32_bf16 v[14:17], v[146:149], v[178:181], v[14:17]
	v_mfma_f32_16x16x32_bf16 v[10:13], v[154:157], v[178:181], v[10:13]
	v_mfma_f32_16x16x32_bf16 v[6:9], v[146:149], v[182:185], v[6:9]
	v_mfma_f32_16x16x32_bf16 v[2:5], v[154:157], v[182:185], v[2:5]
	v_mfma_f32_16x16x32_bf16 v[30:33], v[150:153], v[170:173], v[30:33]
	v_mfma_f32_16x16x32_bf16 v[26:29], v[158:161], v[170:173], v[26:29]
	v_mfma_f32_16x16x32_bf16 v[22:25], v[150:153], v[174:177], v[22:25]
	v_mfma_f32_16x16x32_bf16 v[18:21], v[158:161], v[174:177], v[18:21]
	v_mfma_f32_16x16x32_bf16 v[14:17], v[150:153], v[186:189], v[14:17]
	v_mfma_f32_16x16x32_bf16 v[10:13], v[158:161], v[186:189], v[10:13]
	v_mfma_f32_16x16x32_bf16 v[6:9], v[150:153], v[190:193], v[6:9]
	v_mfma_f32_16x16x32_bf16 v[2:5], v[158:161], v[190:193], v[2:5]
	s_setprio 0
	s_barrier
	s_add_i32 s33, s33, 2
	s_addk_i32 s53, 0x100
	s_cmp_gt_u32 s33, 13
	s_cbranch_scc0 .LBB0_1122
.LBB0_1125:
	s_mov_b32 m0, s44
	s_add_i32 s4, s4, 0x40080
	s_mov_b32 s8, s70
	buffer_load_dwordx4 v1, s[8:11], s4 offen lds
	s_mov_b32 m0, s45
	v_mov_b32_e32 v130, v236
	v_mov_b32_e32 v131, v237
	buffer_load_dwordx4 v234, s[8:11], s4 offen lds
	s_lshl_b32 s4, s21, 8
	v_add_u32_e32 v136, s42, v130
	v_lshl_add_u32 v132, s20, 8, v136
	s_or_b32 s4, s4, s43
	v_add_u32_e32 v134, 0x80, v132
	v_lshl_add_u32 v130, v131, 3, s4
	v_ashrrev_i32_e32 v135, 31, v134
	v_lshlrev_b64 v[134:135], 13, v[134:135]
	v_ashrrev_i32_e32 v131, 31, v130
	s_lshl_b32 s4, s34, 10
	v_lshl_add_u64 v[134:135], s[72:73], 0, v[134:135]
	v_lshlrev_b64 v[130:131], 1, v[130:131]
	s_add_i32 s4, s4, 0
	v_lshl_add_u64 v[230:231], v[134:135], 0, v[130:131]
	v_lshl_add_u32 v134, v136, 2, s4
	v_add_u32_e32 v150, 0x20100, v134
	ds_read_b32 v138, v150
	v_ashrrev_i32_e32 v133, 31, v132
	v_max_f32 v134, 0, v126
	v_max_f32 v136, 0, v122
	v_max_f32 v135, 0, v127
	v_max_f32 v137, 0, v123
	v_lshlrev_b64 v[140:141], 13, v[132:133]
	v_max_f32 v142, 0, v128
	v_max_f32 v144, 0, v124
	v_max_f32 v143, 0, v129
	v_max_f32 v145, 0, v125
	v_pk_mul_f32 v[136:137], v[122:123], v[136:137]
	v_pk_mul_f32 v[134:135], v[126:127], v[134:135]
	v_pk_mul_f32 v[144:145], v[124:125], v[144:145]
	s_waitcnt lgkmcnt(0)
	v_pk_mul_f32 v[136:137], v[138:139], v[136:137] op_sel_hi:[0,1]
	v_pk_mul_f32 v[142:143], v[128:129], v[142:143]
	v_pk_mul_f32 v[134:135], v[138:139], v[134:135] op_sel_hi:[0,1]
	v_lshl_add_u64 v[140:141], s[72:73], 0, v[140:141]
	v_pk_mul_f32 v[144:145], v[138:139], v[144:145] op_sel_hi:[0,1]
	v_pk_mul_f32 v[142:143], v[138:139], v[142:143] op_sel_hi:[0,1]
	v_cvt_pk_bf16_f32 v134, v134, v135
	v_cvt_pk_bf16_f32 v135, v142, v143
	v_cvt_pk_bf16_f32 v136, v136, v137
	v_cvt_pk_bf16_f32 v137, v144, v145
	v_lshl_add_u64 v[140:141], v[140:141], 0, v[130:131]
	global_store_dwordx4 v[140:141], v[134:137], off nt
	v_max_f32 v142, 0, v96
	v_max_f32 v144, 0, v92
	v_max_f32 v143, 0, v97
	v_max_f32 v145, 0, v93
	v_max_f32 v146, 0, v52
	s_nop 1
	v_max_f32 v134, 0, v94
	v_max_f32 v136, 0, v90
	v_max_f32 v135, 0, v95
	v_max_f32 v137, 0, v91
	v_pk_mul_f32 v[144:145], v[92:93], v[144:145]
	v_pk_mul_f32 v[136:137], v[90:91], v[136:137]
	v_pk_mul_f32 v[134:135], v[94:95], v[134:135]
	v_pk_mul_f32 v[136:137], v[138:139], v[136:137] op_sel_hi:[0,1]
	v_pk_mul_f32 v[142:143], v[96:97], v[142:143]
	v_pk_mul_f32 v[134:135], v[138:139], v[134:135] op_sel_hi:[0,1]
	v_pk_mul_f32 v[144:145], v[138:139], v[144:145] op_sel_hi:[0,1]
	v_pk_mul_f32 v[142:143], v[138:139], v[142:143] op_sel_hi:[0,1]
	v_cvt_pk_bf16_f32 v134, v134, v135
	v_cvt_pk_bf16_f32 v135, v142, v143
	v_cvt_pk_bf16_f32 v136, v136, v137
	v_cvt_pk_bf16_f32 v137, v144, v145
	ds_read_b32 v138, v150 offset:64
	global_store_dwordx4 v[140:141], v[134:137], off offset:256 nt
	v_max_f32 v142, 0, v120
	v_max_f32 v144, 0, v116
	v_max_f32 v143, 0, v121
	v_max_f32 v145, 0, v117
	v_max_f32 v147, 0, v53
	s_nop 1
	v_add_u32_e32 v134, 16, v132
	v_ashrrev_i32_e32 v135, 31, v134
	v_lshlrev_b64 v[140:141], 13, v[134:135]
	v_max_f32 v134, 0, v118
	v_max_f32 v136, 0, v114
	v_max_f32 v135, 0, v119
	v_max_f32 v137, 0, v115
	v_pk_mul_f32 v[144:145], v[116:117], v[144:145]
	v_pk_mul_f32 v[136:137], v[114:115], v[136:137]
	v_pk_mul_f32 v[134:135], v[118:119], v[134:135]
	s_waitcnt lgkmcnt(0)
	v_pk_mul_f32 v[136:137], v[138:139], v[136:137] op_sel_hi:[0,1]
	v_pk_mul_f32 v[142:143], v[120:121], v[142:143]
	v_pk_mul_f32 v[134:135], v[138:139], v[134:135] op_sel_hi:[0,1]
	v_lshl_add_u64 v[140:141], s[72:73], 0, v[140:141]
	v_pk_mul_f32 v[144:145], v[138:139], v[144:145] op_sel_hi:[0,1]
	v_pk_mul_f32 v[142:143], v[138:139], v[142:143] op_sel_hi:[0,1]
	v_cvt_pk_bf16_f32 v134, v134, v135
	v_cvt_pk_bf16_f32 v135, v142, v143
	v_cvt_pk_bf16_f32 v136, v136, v137
	v_cvt_pk_bf16_f32 v137, v144, v145
	v_lshl_add_u64 v[140:141], v[140:141], 0, v[130:131]
	global_store_dwordx4 v[140:141], v[134:137], off nt
	v_max_f32 v142, 0, v88
	v_max_f32 v144, 0, v84
	v_max_f32 v143, 0, v89
	v_max_f32 v145, 0, v85
	v_pk_mul_f32 v[146:147], v[52:53], v[146:147]
	s_nop 0
	v_max_f32 v134, 0, v86
	v_max_f32 v136, 0, v82
	v_max_f32 v135, 0, v87
	v_max_f32 v137, 0, v83
	v_pk_mul_f32 v[144:145], v[84:85], v[144:145]
	v_pk_mul_f32 v[136:137], v[82:83], v[136:137]
	v_pk_mul_f32 v[134:135], v[86:87], v[134:135]
	v_pk_mul_f32 v[136:137], v[138:139], v[136:137] op_sel_hi:[0,1]
	v_pk_mul_f32 v[142:143], v[88:89], v[142:143]
	v_pk_mul_f32 v[134:135], v[138:139], v[134:135] op_sel_hi:[0,1]
	v_pk_mul_f32 v[144:145], v[138:139], v[144:145] op_sel_hi:[0,1]
	v_pk_mul_f32 v[142:143], v[138:139], v[142:143] op_sel_hi:[0,1]
	v_cvt_pk_bf16_f32 v134, v134, v135
	v_cvt_pk_bf16_f32 v135, v142, v143
	v_cvt_pk_bf16_f32 v136, v136, v137
	v_cvt_pk_bf16_f32 v137, v144, v145
	ds_read_b32 v138, v150 offset:128
	global_store_dwordx4 v[140:141], v[134:137], off offset:256 nt
	v_max_f32 v142, 0, v112
	v_max_f32 v144, 0, v108
	v_max_f32 v143, 0, v113
	v_max_f32 v145, 0, v109
	v_max_f32 v158, 0, v16
	s_nop 1
	v_add_u32_e32 v134, 32, v132
	v_ashrrev_i32_e32 v135, 31, v134
	v_lshlrev_b64 v[140:141], 13, v[134:135]
	v_max_f32 v134, 0, v110
	v_max_f32 v136, 0, v106
	v_max_f32 v135, 0, v111
	v_max_f32 v137, 0, v107
	v_pk_mul_f32 v[144:145], v[108:109], v[144:145]
	v_pk_mul_f32 v[136:137], v[106:107], v[136:137]
	v_pk_mul_f32 v[134:135], v[110:111], v[134:135]
	s_waitcnt lgkmcnt(0)
	v_pk_mul_f32 v[136:137], v[138:139], v[136:137] op_sel_hi:[0,1]
	v_pk_mul_f32 v[142:143], v[112:113], v[142:143]
	v_pk_mul_f32 v[134:135], v[138:139], v[134:135] op_sel_hi:[0,1]
	v_lshl_add_u64 v[140:141], s[72:73], 0, v[140:141]
	v_pk_mul_f32 v[144:145], v[138:139], v[144:145] op_sel_hi:[0,1]
	v_pk_mul_f32 v[142:143], v[138:139], v[142:143] op_sel_hi:[0,1]
	v_cvt_pk_bf16_f32 v134, v134, v135
	v_cvt_pk_bf16_f32 v135, v142, v143
	v_cvt_pk_bf16_f32 v136, v136, v137
	v_cvt_pk_bf16_f32 v137, v144, v145
	v_lshl_add_u64 v[140:141], v[140:141], 0, v[130:131]
	global_store_dwordx4 v[140:141], v[134:137], off nt
	v_max_f32 v142, 0, v80
	v_max_f32 v143, 0, v81
	v_max_f32 v144, 0, v76
	v_max_f32 v145, 0, v77
	v_add_u32_e32 v132, 48, v132
	s_nop 0
	v_max_f32 v134, 0, v78
	v_max_f32 v136, 0, v74
	v_max_f32 v135, 0, v79
	v_max_f32 v137, 0, v75
	v_pk_mul_f32 v[142:143], v[80:81], v[142:143]
	v_pk_mul_f32 v[136:137], v[74:75], v[136:137]
	v_pk_mul_f32 v[134:135], v[78:79], v[134:135]
	v_pk_mul_f32 v[136:137], v[138:139], v[136:137] op_sel_hi:[0,1]
	v_pk_mul_f32 v[134:135], v[138:139], v[134:135] op_sel_hi:[0,1]
	v_pk_mul_f32 v[144:145], v[76:77], v[144:145]
	v_pk_mul_f32 v[142:143], v[138:139], v[142:143] op_sel_hi:[0,1]
	v_cvt_pk_bf16_f32 v134, v134, v135
	v_cvt_pk_bf16_f32 v135, v142, v143
	v_cvt_pk_bf16_f32 v136, v136, v137
	v_pk_mul_f32 v[144:145], v[138:139], v[144:145] op_sel_hi:[0,1]
	v_cvt_pk_bf16_f32 v137, v144, v145
	global_store_dwordx4 v[140:141], v[134:137], off offset:256 nt
	ds_read_b32 v136, v150 offset:192
	v_ashrrev_i32_e32 v133, 31, v132
	v_lshlrev_b64 v[138:139], 13, v[132:133]
	v_max_f32 v132, 0, v102
	v_max_f32 v134, 0, v98
	v_max_f32 v133, 0, v103
	v_max_f32 v135, 0, v99
	v_max_f32 v140, 0, v104
	v_max_f32 v142, 0, v100
	v_max_f32 v141, 0, v105
	v_max_f32 v143, 0, v101
	s_nop 0
	v_pk_mul_f32 v[132:133], v[102:103], v[132:133]
	v_pk_mul_f32 v[134:135], v[98:99], v[134:135]
	v_pk_mul_f32 v[142:143], v[100:101], v[142:143]
	s_waitcnt lgkmcnt(0)
	v_pk_mul_f32 v[134:135], v[136:137], v[134:135] op_sel_hi:[0,1]
	v_pk_mul_f32 v[140:141], v[104:105], v[140:141]
	v_pk_mul_f32 v[132:133], v[136:137], v[132:133] op_sel_hi:[0,1]
	v_lshl_add_u64 v[138:139], s[72:73], 0, v[138:139]
	v_pk_mul_f32 v[142:143], v[136:137], v[142:143] op_sel_hi:[0,1]
	v_pk_mul_f32 v[140:141], v[136:137], v[140:141] op_sel_hi:[0,1]
	v_cvt_pk_bf16_f32 v132, v132, v133
	v_cvt_pk_bf16_f32 v133, v140, v141
	v_cvt_pk_bf16_f32 v134, v134, v135
	v_cvt_pk_bf16_f32 v135, v142, v143
	v_lshl_add_u64 v[138:139], v[138:139], 0, v[130:131]
	global_store_dwordx4 v[138:139], v[132:135], off nt
	v_max_f32 v130, 0, v70
	v_max_f32 v131, 0, v71
	v_max_f32 v140, 0, v68
	v_max_f32 v141, 0, v69
	v_max_f32 v142, 0, v28
	s_nop 1
	v_max_f32 v132, 0, v66
	v_max_f32 v133, 0, v67
	v_max_f32 v134, 0, v72
	v_max_f32 v135, 0, v73
	v_pk_mul_f32 v[130:131], v[70:71], v[130:131]
	v_pk_mul_f32 v[132:133], v[66:67], v[132:133]
	v_pk_mul_f32 v[134:135], v[72:73], v[134:135]
	v_pk_mul_f32 v[140:141], v[68:69], v[140:141]
	v_pk_mul_f32 v[132:133], v[136:137], v[132:133] op_sel_hi:[0,1]
	v_pk_mul_f32 v[134:135], v[136:137], v[134:135] op_sel_hi:[0,1]
	v_pk_mul_f32 v[130:131], v[136:137], v[130:131] op_sel_hi:[0,1]
	v_pk_mul_f32 v[140:141], v[136:137], v[140:141] op_sel_hi:[0,1]
	v_cvt_pk_bf16_f32 v130, v130, v131
	v_cvt_pk_bf16_f32 v131, v134, v135
	v_cvt_pk_bf16_f32 v132, v132, v133
	v_cvt_pk_bf16_f32 v133, v140, v141
	ds_read_b32 v134, v150 offset:512
	global_store_dwordx4 v[138:139], v[130:133], off offset:256 nt
	v_max_f32 v138, 0, v60
	v_max_f32 v139, 0, v61
	v_max_f32 v136, 0, v64
	v_max_f32 v137, 0, v65
	v_max_f32 v143, 0, v29
	s_nop 1
	v_max_f32 v130, 0, v62
	v_max_f32 v132, 0, v58
	v_max_f32 v131, 0, v63
	v_max_f32 v133, 0, v59
	v_pk_mul_f32 v[138:139], v[60:61], v[138:139]
	v_pk_mul_f32 v[132:133], v[58:59], v[132:133]
	v_pk_mul_f32 v[130:131], v[62:63], v[130:131]
	s_waitcnt lgkmcnt(0)
	v_pk_mul_f32 v[138:139], v[134:135], v[138:139] op_sel_hi:[0,1]
	v_pk_mul_f32 v[132:133], v[134:135], v[132:133] op_sel_hi:[0,1]
	v_pk_mul_f32 v[136:137], v[64:65], v[136:137]
	v_pk_mul_f32 v[130:131], v[134:135], v[130:131] op_sel_hi:[0,1]
	v_pk_mul_f32 v[136:137], v[134:135], v[136:137] op_sel_hi:[0,1]
	v_cvt_pk_bf16_f32 v130, v130, v131
	v_cvt_pk_bf16_f32 v131, v136, v137
	v_cvt_pk_bf16_f32 v132, v132, v133
	v_cvt_pk_bf16_f32 v133, v138, v139
	v_max_f32 v138, 0, v26
	v_max_f32 v139, 0, v27
	v_max_f32 v136, 0, v30
	v_max_f32 v137, 0, v31
	v_max_f32 v140, 0, v32
	v_max_f32 v141, 0, v33
	v_pk_mul_f32 v[142:143], v[28:29], v[142:143]
	v_pk_mul_f32 v[138:139], v[26:27], v[138:139]
	v_pk_mul_f32 v[136:137], v[30:31], v[136:137]
	v_pk_mul_f32 v[144:145], v[134:135], v[138:139] op_sel_hi:[0,1]
	v_pk_mul_f32 v[138:139], v[32:33], v[140:141]
	v_pk_mul_f32 v[142:143], v[134:135], v[142:143] op_sel_hi:[0,1]
	v_pk_mul_f32 v[140:141], v[134:135], v[138:139] op_sel_hi:[0,1]
	v_pk_mul_f32 v[134:135], v[134:135], v[136:137] op_sel_hi:[0,1]
	v_cvt_pk_bf16_f32 v138, v134, v135
	v_cvt_pk_bf16_f32 v139, v140, v141
	v_cvt_pk_bf16_f32 v140, v144, v145
	v_cvt_pk_bf16_f32 v141, v142, v143
	ds_read_b32 v134, v150 offset:576
	v_max_f32 v142, 0, v50
	v_max_f32 v143, 0, v51
	v_max_f32 v136, 0, v54
	v_max_f32 v137, 0, v55
	v_max_f32 v144, 0, v56
	v_max_f32 v145, 0, v57
	s_waitcnt lgkmcnt(0)
	v_pk_mul_f32 v[152:153], v[134:135], v[146:147] op_sel_hi:[0,1]
	v_pk_mul_f32 v[142:143], v[50:51], v[142:143]
	v_pk_mul_f32 v[144:145], v[56:57], v[144:145]
	v_pk_mul_f32 v[142:143], v[134:135], v[142:143] op_sel_hi:[0,1]
	v_pk_mul_f32 v[136:137], v[54:55], v[136:137]
	v_pk_mul_f32 v[144:145], v[134:135], v[144:145] op_sel_hi:[0,1]
	v_pk_mul_f32 v[136:137], v[134:135], v[136:137] op_sel_hi:[0,1]
	v_cvt_pk_bf16_f32 v146, v136, v137
	v_cvt_pk_bf16_f32 v147, v144, v145
	v_cvt_pk_bf16_f32 v148, v142, v143
	v_max_f32 v142, 0, v18
	v_max_f32 v143, 0, v19
	v_cvt_pk_bf16_f32 v149, v152, v153
	v_max_f32 v136, 0, v22
	v_max_f32 v137, 0, v23
	v_max_f32 v144, 0, v24
	v_max_f32 v152, 0, v20
	v_max_f32 v145, 0, v25
	v_max_f32 v153, 0, v21
	s_nop 0
	v_pk_mul_f32 v[142:143], v[18:19], v[142:143]
	v_pk_mul_f32 v[152:153], v[20:21], v[152:153]
	v_pk_mul_f32 v[142:143], v[134:135], v[142:143] op_sel_hi:[0,1]
	v_pk_mul_f32 v[144:145], v[24:25], v[144:145]
	v_pk_mul_f32 v[136:137], v[22:23], v[136:137]
	v_pk_mul_f32 v[152:153], v[134:135], v[152:153] op_sel_hi:[0,1]
	v_pk_mul_f32 v[144:145], v[134:135], v[144:145] op_sel_hi:[0,1]
	v_pk_mul_f32 v[134:135], v[134:135], v[136:137] op_sel_hi:[0,1]
	v_cvt_pk_bf16_f32 v154, v134, v135
	v_cvt_pk_bf16_f32 v155, v144, v145
	v_cvt_pk_bf16_f32 v156, v142, v143
	v_cvt_pk_bf16_f32 v157, v152, v153
	ds_read_b32 v142, v150 offset:640
	v_max_f32 v134, 0, v46
	v_max_f32 v136, 0, v42
	v_max_f32 v135, 0, v47
	v_max_f32 v137, 0, v43
	v_max_f32 v144, 0, v48
	v_max_f32 v152, 0, v44
	v_max_f32 v145, 0, v49
	v_max_f32 v153, 0, v45
	s_nop 0
	v_pk_mul_f32 v[134:135], v[46:47], v[134:135]
	v_pk_mul_f32 v[152:153], v[44:45], v[152:153]
	v_pk_mul_f32 v[136:137], v[42:43], v[136:137]
	v_pk_mul_f32 v[144:145], v[48:49], v[144:145]
	s_waitcnt lgkmcnt(0)
	v_pk_mul_f32 v[152:153], v[142:143], v[152:153] op_sel_hi:[0,1]
	v_pk_mul_f32 v[136:137], v[142:143], v[136:137] op_sel_hi:[0,1]
	v_pk_mul_f32 v[144:145], v[142:143], v[144:145] op_sel_hi:[0,1]
	v_pk_mul_f32 v[134:135], v[142:143], v[134:135] op_sel_hi:[0,1]
	v_cvt_pk_bf16_f32 v134, v134, v135
	v_cvt_pk_bf16_f32 v135, v144, v145
	v_cvt_pk_bf16_f32 v136, v136, v137
	v_cvt_pk_bf16_f32 v137, v152, v153
	v_max_f32 v144, 0, v14
	v_max_f32 v152, 0, v10
	v_max_f32 v145, 0, v15
	v_max_f32 v153, 0, v11
	v_max_f32 v160, 0, v12
	v_max_f32 v159, 0, v17
	v_max_f32 v161, 0, v13
	v_max_f32 v151, 0, v39
	s_nop 0
	v_pk_mul_f32 v[144:145], v[14:15], v[144:145]
	v_pk_mul_f32 v[160:161], v[12:13], v[160:161]
	v_pk_mul_f32 v[152:153], v[10:11], v[152:153]
	v_pk_mul_f32 v[158:159], v[16:17], v[158:159]
	v_pk_mul_f32 v[160:161], v[142:143], v[160:161] op_sel_hi:[0,1]
	v_pk_mul_f32 v[152:153], v[142:143], v[152:153] op_sel_hi:[0,1]
	v_pk_mul_f32 v[158:159], v[142:143], v[158:159] op_sel_hi:[0,1]
	v_pk_mul_f32 v[142:143], v[142:143], v[144:145] op_sel_hi:[0,1]
	v_cvt_pk_bf16_f32 v142, v142, v143
	v_cvt_pk_bf16_f32 v143, v158, v159
	v_cvt_pk_bf16_f32 v144, v152, v153
	v_cvt_pk_bf16_f32 v145, v160, v161
	ds_read_b32 v158, v150 offset:704
	v_max_f32 v150, 0, v38
	v_max_f32 v152, 0, v34
	v_max_f32 v153, 0, v35
	v_max_f32 v160, 0, v40
	v_max_f32 v162, 0, v36
	v_max_f32 v161, 0, v41
	v_max_f32 v163, 0, v37
	s_nop 0
	v_pk_mul_f32 v[150:151], v[38:39], v[150:151]
	v_pk_mul_f32 v[162:163], v[36:37], v[162:163]
	v_pk_mul_f32 v[152:153], v[34:35], v[152:153]
	v_pk_mul_f32 v[160:161], v[40:41], v[160:161]
	s_waitcnt lgkmcnt(0)
	v_pk_mul_f32 v[162:163], v[158:159], v[162:163] op_sel_hi:[0,1]
	v_pk_mul_f32 v[152:153], v[158:159], v[152:153] op_sel_hi:[0,1]
	v_pk_mul_f32 v[160:161], v[158:159], v[160:161] op_sel_hi:[0,1]
	v_pk_mul_f32 v[150:151], v[158:159], v[150:151] op_sel_hi:[0,1]
	v_cvt_pk_bf16_f32 v150, v150, v151
	v_cvt_pk_bf16_f32 v151, v160, v161
	v_cvt_pk_bf16_f32 v152, v152, v153
	v_cvt_pk_bf16_f32 v153, v162, v163
	v_max_f32 v160, 0, v6
	v_max_f32 v162, 0, v2
	v_max_f32 v161, 0, v7
	v_max_f32 v163, 0, v3
	v_max_f32 v164, 0, v8
	v_max_f32 v166, 0, v4
	v_max_f32 v165, 0, v9
	v_max_f32 v167, 0, v5
	s_nop 0
	v_pk_mul_f32 v[160:161], v[6:7], v[160:161]
	v_pk_mul_f32 v[166:167], v[4:5], v[166:167]
	v_pk_mul_f32 v[162:163], v[2:3], v[162:163]
	v_pk_mul_f32 v[164:165], v[8:9], v[164:165]
	v_pk_mul_f32 v[166:167], v[158:159], v[166:167] op_sel_hi:[0,1]
	v_pk_mul_f32 v[162:163], v[158:159], v[162:163] op_sel_hi:[0,1]
	v_pk_mul_f32 v[164:165], v[158:159], v[164:165] op_sel_hi:[0,1]
	v_pk_mul_f32 v[158:159], v[158:159], v[160:161] op_sel_hi:[0,1]
	v_cvt_pk_bf16_f32 v158, v158, v159
	v_cvt_pk_bf16_f32 v159, v164, v165
	v_cvt_pk_bf16_f32 v160, v162, v163
	v_cndmask_b32_e64 v162, 0, 1, s[2:3]
	v_cmp_ne_u32_e64 s[4:5], 1, v162
	s_andn2_b64 vcc, exec, s[2:3]
	s_mov_b64 s[2:3], -1
	v_cvt_pk_bf16_f32 v161, v166, v167
	s_cbranch_vccnz .LBB0_1127
	v_add_co_u32_e32 v162, vcc, 0x20000, v230
	global_store_dwordx4 v[230:231], v[130:133], off nt
	global_store_dwordx4 v[230:231], v[138:141], off offset:256 nt
	v_addc_co_u32_e32 v163, vcc, 0, v231, vcc
	global_store_dwordx4 v[162:163], v[146:149], off nt
	global_store_dwordx4 v[162:163], v[154:157], off offset:256 nt
	v_add_co_u32_e32 v162, vcc, 0x40000, v230
	s_nop 1
	v_addc_co_u32_e32 v163, vcc, 0, v231, vcc
	global_store_dwordx4 v[162:163], v[134:137], off nt
	global_store_dwordx4 v[162:163], v[142:145], off offset:256 nt
	v_add_co_u32_e32 v162, vcc, 0x60000, v230
	s_nop 1
	v_addc_co_u32_e32 v163, vcc, 0, v231, vcc
	global_store_dwordx4 v[162:163], v[150:153], off nt
	global_store_dwordx4 v[162:163], v[158:161], off offset:256 nt
	s_cbranch_execnz .LBB0_1096
	s_branch .LBB0_1128
.LBB0_1127:
	s_andn2_b64 vcc, exec, s[2:3]
	s_cbranch_vccnz .LBB0_1096
.LBB0_1128:
	s_branch .LBB0_1095
.LBB0_1130:
	s_cmp_lg_u64 s[16:17], 0
	s_cbranch_scc0 my_skew_p5
	s_barrier
my_skew_p5:
	s_waitcnt vmcnt(0)
	s_barrier
